# HGRN2 prompt scan: three 8-chunk groups of loads kept in flight (counted vmcnt), scalar-base addressing
# speedup vs baseline: 1.0043x; 1.0040x over previous
; DI float bf2f(u16 h) { return __uint_as_float(((unsigned)h) << 16); }
; DI void hgrn_scan_phase(const Params& p, char* smem) {
;     ...
;   for (int it = blockIdx.x; it < 512; it += gridDim.x) {
;     const int hd = it >> 6, v = (it & 63) * 2 + (tid >> 7), k = tid & 127;
;     u16* up = U + ((long)hd * 128 + v) * 128 + k;
;     const float* dp = decay + hd * 128 + k;
;     float S = 0.f;
;     float cu[8], cd[8];
; #pragma unroll
;     for (int j = 0; j < 8; j++) { cu[j] = bf2f(up[(long)j * 131072]); cd[j] = dp[j * 1024]; }
;     for (int n0 = 0; n0 < 256; n0 += 8) {
;       float nu[8], nd[8];
;       if (n0 + 8 < 256) {
; #pragma unroll
;         for (int j = 0; j < 8; j++) { nu[j] = bf2f(up[(long)(n0 + 8 + j) * 131072]); nd[j] = dp[(n0 + 8 + j) * 1024]; }
.LBB0_1336:
	s_lshl_b32 s20, s38, 1
	s_ashr_i32 s22, s38, 6
	s_and_b32 s20, s20, 0x7e
	v_add_u32_e32 v36, s20, v24
	s_ashr_i32 s23, s22, 31
	s_lshl_b64 s[20:21], s[22:23], 7
	v_ashrrev_i32_e32 v37, 31, v36
	v_add_u32_e32 v2, s20, v36
	v_lshlrev_b32_e32 v2, 8, v2
	v_add_u32_e32 v2, v2, v28
	s_lshl_b32 s22, s22, 9
	v_or_b32_e32 v3, s22, v32
	s_mov_b64 s[98:99], s[0:1]
	s_mov_b64 s[100:101], s[12:13]
	s_mov_b64 s[40:41], s[0:1]
	v_mov_b32_e32 v15, 0
	global_load_ushort v60, v2, s[98:99]
	global_load_dword v68, v3, s[100:101]
	s_add_u32 s98, s98, 0x40000
	s_addc_u32 s99, s99, 0
	s_add_u32 s100, s100, 0x1000
	s_addc_u32 s101, s101, 0
	global_load_ushort v61, v2, s[98:99]
	global_load_dword v69, v3, s[100:101]
	s_add_u32 s98, s98, 0x40000
	s_addc_u32 s99, s99, 0
	s_add_u32 s100, s100, 0x1000
	s_addc_u32 s101, s101, 0
	global_load_ushort v62, v2, s[98:99]
	global_load_dword v70, v3, s[100:101]
	s_add_u32 s98, s98, 0x40000
	s_addc_u32 s99, s99, 0
	s_add_u32 s100, s100, 0x1000
	s_addc_u32 s101, s101, 0
	global_load_ushort v63, v2, s[98:99]
	global_load_dword v71, v3, s[100:101]
	s_add_u32 s98, s98, 0x40000
	s_addc_u32 s99, s99, 0
	s_add_u32 s100, s100, 0x1000
	s_addc_u32 s101, s101, 0
	global_load_ushort v64, v2, s[98:99]
	global_load_dword v72, v3, s[100:101]
	s_add_u32 s98, s98, 0x40000
	s_addc_u32 s99, s99, 0
	s_add_u32 s100, s100, 0x1000
	s_addc_u32 s101, s101, 0
	global_load_ushort v65, v2, s[98:99]
	global_load_dword v73, v3, s[100:101]
	s_add_u32 s98, s98, 0x40000
	s_addc_u32 s99, s99, 0
	s_add_u32 s100, s100, 0x1000
	s_addc_u32 s101, s101, 0
	global_load_ushort v66, v2, s[98:99]
	global_load_dword v74, v3, s[100:101]
	s_add_u32 s98, s98, 0x40000
	s_addc_u32 s99, s99, 0
	s_add_u32 s100, s100, 0x1000
	s_addc_u32 s101, s101, 0
	global_load_ushort v67, v2, s[98:99]
	global_load_dword v75, v3, s[100:101]
	s_add_u32 s98, s98, 0x40000
	s_addc_u32 s99, s99, 0
	s_add_u32 s100, s100, 0x1000
	s_addc_u32 s101, s101, 0
	global_load_ushort v76, v2, s[98:99]
	global_load_dword v84, v3, s[100:101]
	s_add_u32 s98, s98, 0x40000
	s_addc_u32 s99, s99, 0
	s_add_u32 s100, s100, 0x1000
	s_addc_u32 s101, s101, 0
	global_load_ushort v77, v2, s[98:99]
	global_load_dword v85, v3, s[100:101]
	s_add_u32 s98, s98, 0x40000
	s_addc_u32 s99, s99, 0
	s_add_u32 s100, s100, 0x1000
	s_addc_u32 s101, s101, 0
	global_load_ushort v78, v2, s[98:99]
	global_load_dword v86, v3, s[100:101]
	s_add_u32 s98, s98, 0x40000
	s_addc_u32 s99, s99, 0
	s_add_u32 s100, s100, 0x1000
	s_addc_u32 s101, s101, 0
	global_load_ushort v79, v2, s[98:99]
	global_load_dword v87, v3, s[100:101]
	s_add_u32 s98, s98, 0x40000
	s_addc_u32 s99, s99, 0
	s_add_u32 s100, s100, 0x1000
	s_addc_u32 s101, s101, 0
	global_load_ushort v80, v2, s[98:99]
	global_load_dword v88, v3, s[100:101]
	s_add_u32 s98, s98, 0x40000
	s_addc_u32 s99, s99, 0
	s_add_u32 s100, s100, 0x1000
	s_addc_u32 s101, s101, 0
	global_load_ushort v81, v2, s[98:99]
	global_load_dword v89, v3, s[100:101]
	s_add_u32 s98, s98, 0x40000
	s_addc_u32 s99, s99, 0
	s_add_u32 s100, s100, 0x1000
	s_addc_u32 s101, s101, 0
	global_load_ushort v82, v2, s[98:99]
	global_load_dword v90, v3, s[100:101]
	s_add_u32 s98, s98, 0x40000
	s_addc_u32 s99, s99, 0
	s_add_u32 s100, s100, 0x1000
	s_addc_u32 s101, s101, 0
	global_load_ushort v83, v2, s[98:99]
	global_load_dword v91, v3, s[100:101]
	s_add_u32 s98, s98, 0x40000
	s_addc_u32 s99, s99, 0
	s_add_u32 s100, s100, 0x1000
	s_addc_u32 s101, s101, 0
	global_load_ushort v92, v2, s[98:99]
	global_load_dword v100, v3, s[100:101]
	s_add_u32 s98, s98, 0x40000
	s_addc_u32 s99, s99, 0
	s_add_u32 s100, s100, 0x1000
	s_addc_u32 s101, s101, 0
	global_load_ushort v93, v2, s[98:99]
	global_load_dword v101, v3, s[100:101]
	s_add_u32 s98, s98, 0x40000
	s_addc_u32 s99, s99, 0
	s_add_u32 s100, s100, 0x1000
	s_addc_u32 s101, s101, 0
	global_load_ushort v94, v2, s[98:99]
	global_load_dword v102, v3, s[100:101]
	s_add_u32 s98, s98, 0x40000
	s_addc_u32 s99, s99, 0
	s_add_u32 s100, s100, 0x1000
	s_addc_u32 s101, s101, 0
	global_load_ushort v95, v2, s[98:99]
	global_load_dword v103, v3, s[100:101]
	s_add_u32 s98, s98, 0x40000
	s_addc_u32 s99, s99, 0
	s_add_u32 s100, s100, 0x1000
	s_addc_u32 s101, s101, 0
	global_load_ushort v96, v2, s[98:99]
	global_load_dword v104, v3, s[100:101]
	s_add_u32 s98, s98, 0x40000
	s_addc_u32 s99, s99, 0
	s_add_u32 s100, s100, 0x1000
	s_addc_u32 s101, s101, 0
	global_load_ushort v97, v2, s[98:99]
	global_load_dword v105, v3, s[100:101]
	s_add_u32 s98, s98, 0x40000
	s_addc_u32 s99, s99, 0
	s_add_u32 s100, s100, 0x1000
	s_addc_u32 s101, s101, 0
	global_load_ushort v98, v2, s[98:99]
	global_load_dword v106, v3, s[100:101]
	s_add_u32 s98, s98, 0x40000
	s_addc_u32 s99, s99, 0
	s_add_u32 s100, s100, 0x1000
	s_addc_u32 s101, s101, 0
	global_load_ushort v99, v2, s[98:99]
	global_load_dword v107, v3, s[100:101]
	s_add_u32 s98, s98, 0x40000
	s_addc_u32 s99, s99, 0
	s_add_u32 s100, s100, 0x1000
	s_addc_u32 s101, s101, 0
	s_waitcnt vmcnt(32)
; DI u16 f2bf(float x) { return (u16)(pack2(x, 0.f) & 0xffffu); }
; DI float bf2f(u16 h) { return __uint_as_float(((unsigned)h) << 16); }
; DI void hgrn_scan_phase(const Params& p, char* smem) {
;     ...
;     for (int n0 = 0; n0 < 256; n0 += 8) {
;       float nu[8], nd[8];
;       if (n0 + 8 < 256) {
; #pragma unroll
;         for (int j = 0; j < 8; j++) { nu[j] = bf2f(up[(long)(n0 + 8 + j) * 131072]); nd[j] = dp[(n0 + 8 + j) * 1024]; }
;       } else {
; #pragma unroll
;         for (int j = 0; j < 8; j++) { nu[j] = 0.f; nd[j] = 0.f; }
;       }
; #pragma unroll
;       for (int j = 0; j < 8; j++) { up[(long)(n0 + j) * 131072] = f2bf(S); S = cd[j] * S + cu[j]; }
; #pragma unroll
;       for (int j = 0; j < 8; j++) { cu[j] = nu[j]; cd[j] = nd[j]; }
;     }
	v_cvt_pk_bf16_f32 v50, v15, v15
	v_lshlrev_b32_e32 v54, 16, v60
	global_store_short v2, v50, s[40:41]
	v_fma_f32 v15, v68, v15, v54
	s_add_u32 s40, s40, 0x40000
	s_addc_u32 s41, s41, 0
	v_cvt_pk_bf16_f32 v51, v15, v15
	v_lshlrev_b32_e32 v54, 16, v61
	global_store_short v2, v51, s[40:41]
	v_fma_f32 v15, v69, v15, v54
	s_add_u32 s40, s40, 0x40000
	s_addc_u32 s41, s41, 0
	v_cvt_pk_bf16_f32 v52, v15, v15
	v_lshlrev_b32_e32 v54, 16, v62
	global_store_short v2, v52, s[40:41]
	v_fma_f32 v15, v70, v15, v54
	s_add_u32 s40, s40, 0x40000
	s_addc_u32 s41, s41, 0
	v_cvt_pk_bf16_f32 v53, v15, v15
	v_lshlrev_b32_e32 v54, 16, v63
	global_store_short v2, v53, s[40:41]
	v_fma_f32 v15, v71, v15, v54
	s_add_u32 s40, s40, 0x40000
	s_addc_u32 s41, s41, 0
	v_cvt_pk_bf16_f32 v50, v15, v15
	v_lshlrev_b32_e32 v54, 16, v64
	global_store_short v2, v50, s[40:41]
	v_fma_f32 v15, v72, v15, v54
	s_add_u32 s40, s40, 0x40000
	s_addc_u32 s41, s41, 0
	v_cvt_pk_bf16_f32 v51, v15, v15
	v_lshlrev_b32_e32 v54, 16, v65
	global_store_short v2, v51, s[40:41]
	v_fma_f32 v15, v73, v15, v54
	s_add_u32 s40, s40, 0x40000
	s_addc_u32 s41, s41, 0
	v_cvt_pk_bf16_f32 v52, v15, v15
	v_lshlrev_b32_e32 v54, 16, v66
	global_store_short v2, v52, s[40:41]
	v_fma_f32 v15, v74, v15, v54
	s_add_u32 s40, s40, 0x40000
	s_addc_u32 s41, s41, 0
	v_cvt_pk_bf16_f32 v53, v15, v15
	v_lshlrev_b32_e32 v54, 16, v67
	global_store_short v2, v53, s[40:41]
	v_fma_f32 v15, v75, v15, v54
	s_add_u32 s40, s40, 0x40000
	s_addc_u32 s41, s41, 0
	global_load_ushort v60, v2, s[98:99]
	global_load_dword v68, v3, s[100:101]
	s_add_u32 s98, s98, 0x40000
	s_addc_u32 s99, s99, 0
	s_add_u32 s100, s100, 0x1000
	s_addc_u32 s101, s101, 0
	global_load_ushort v61, v2, s[98:99]
	global_load_dword v69, v3, s[100:101]
	s_add_u32 s98, s98, 0x40000
	s_addc_u32 s99, s99, 0
	s_add_u32 s100, s100, 0x1000
	s_addc_u32 s101, s101, 0
	global_load_ushort v62, v2, s[98:99]
	global_load_dword v70, v3, s[100:101]
	s_add_u32 s98, s98, 0x40000
	s_addc_u32 s99, s99, 0
	s_add_u32 s100, s100, 0x1000
	s_addc_u32 s101, s101, 0
	global_load_ushort v63, v2, s[98:99]
	global_load_dword v71, v3, s[100:101]
	s_add_u32 s98, s98, 0x40000
	s_addc_u32 s99, s99, 0
	s_add_u32 s100, s100, 0x1000
	s_addc_u32 s101, s101, 0
	global_load_ushort v64, v2, s[98:99]
	global_load_dword v72, v3, s[100:101]
	s_add_u32 s98, s98, 0x40000
	s_addc_u32 s99, s99, 0
	s_add_u32 s100, s100, 0x1000
	s_addc_u32 s101, s101, 0
	global_load_ushort v65, v2, s[98:99]
	global_load_dword v73, v3, s[100:101]
	s_add_u32 s98, s98, 0x40000
	s_addc_u32 s99, s99, 0
	s_add_u32 s100, s100, 0x1000
	s_addc_u32 s101, s101, 0
	global_load_ushort v66, v2, s[98:99]
	global_load_dword v74, v3, s[100:101]
	s_add_u32 s98, s98, 0x40000
	s_addc_u32 s99, s99, 0
	s_add_u32 s100, s100, 0x1000
	s_addc_u32 s101, s101, 0
	global_load_ushort v67, v2, s[98:99]
	global_load_dword v75, v3, s[100:101]
	s_add_u32 s98, s98, 0x40000
	s_addc_u32 s99, s99, 0
	s_add_u32 s100, s100, 0x1000
	s_addc_u32 s101, s101, 0
	s_waitcnt vmcnt(40)
	v_cvt_pk_bf16_f32 v50, v15, v15
	v_lshlrev_b32_e32 v54, 16, v76
	global_store_short v2, v50, s[40:41]
	v_fma_f32 v15, v84, v15, v54
	s_add_u32 s40, s40, 0x40000
	s_addc_u32 s41, s41, 0
	v_cvt_pk_bf16_f32 v51, v15, v15
	v_lshlrev_b32_e32 v54, 16, v77
	global_store_short v2, v51, s[40:41]
	v_fma_f32 v15, v85, v15, v54
	s_add_u32 s40, s40, 0x40000
	s_addc_u32 s41, s41, 0
	v_cvt_pk_bf16_f32 v52, v15, v15
	v_lshlrev_b32_e32 v54, 16, v78
	global_store_short v2, v52, s[40:41]
	v_fma_f32 v15, v86, v15, v54
	s_add_u32 s40, s40, 0x40000
	s_addc_u32 s41, s41, 0
	v_cvt_pk_bf16_f32 v53, v15, v15
	v_lshlrev_b32_e32 v54, 16, v79
	global_store_short v2, v53, s[40:41]
	v_fma_f32 v15, v87, v15, v54
	s_add_u32 s40, s40, 0x40000
	s_addc_u32 s41, s41, 0
	v_cvt_pk_bf16_f32 v50, v15, v15
	v_lshlrev_b32_e32 v54, 16, v80
	global_store_short v2, v50, s[40:41]
	v_fma_f32 v15, v88, v15, v54
	s_add_u32 s40, s40, 0x40000
	s_addc_u32 s41, s41, 0
	v_cvt_pk_bf16_f32 v51, v15, v15
	v_lshlrev_b32_e32 v54, 16, v81
	global_store_short v2, v51, s[40:41]
	v_fma_f32 v15, v89, v15, v54
	s_add_u32 s40, s40, 0x40000
	s_addc_u32 s41, s41, 0
	v_cvt_pk_bf16_f32 v52, v15, v15
	v_lshlrev_b32_e32 v54, 16, v82
	global_store_short v2, v52, s[40:41]
	v_fma_f32 v15, v90, v15, v54
	s_add_u32 s40, s40, 0x40000
	s_addc_u32 s41, s41, 0
	v_cvt_pk_bf16_f32 v53, v15, v15
	v_lshlrev_b32_e32 v54, 16, v83
	global_store_short v2, v53, s[40:41]
	v_fma_f32 v15, v91, v15, v54
	s_add_u32 s40, s40, 0x40000
	s_addc_u32 s41, s41, 0
	global_load_ushort v76, v2, s[98:99]
	global_load_dword v84, v3, s[100:101]
	s_add_u32 s98, s98, 0x40000
	s_addc_u32 s99, s99, 0
	s_add_u32 s100, s100, 0x1000
	s_addc_u32 s101, s101, 0
	global_load_ushort v77, v2, s[98:99]
	global_load_dword v85, v3, s[100:101]
	s_add_u32 s98, s98, 0x40000
	s_addc_u32 s99, s99, 0
	s_add_u32 s100, s100, 0x1000
	s_addc_u32 s101, s101, 0
	global_load_ushort v78, v2, s[98:99]
	global_load_dword v86, v3, s[100:101]
	s_add_u32 s98, s98, 0x40000
	s_addc_u32 s99, s99, 0
	s_add_u32 s100, s100, 0x1000
	s_addc_u32 s101, s101, 0
	global_load_ushort v79, v2, s[98:99]
	global_load_dword v87, v3, s[100:101]
	s_add_u32 s98, s98, 0x40000
	s_addc_u32 s99, s99, 0
	s_add_u32 s100, s100, 0x1000
	s_addc_u32 s101, s101, 0
	global_load_ushort v80, v2, s[98:99]
	global_load_dword v88, v3, s[100:101]
	s_add_u32 s98, s98, 0x40000
	s_addc_u32 s99, s99, 0
	s_add_u32 s100, s100, 0x1000
	s_addc_u32 s101, s101, 0
	global_load_ushort v81, v2, s[98:99]
	global_load_dword v89, v3, s[100:101]
	s_add_u32 s98, s98, 0x40000
	s_addc_u32 s99, s99, 0
	s_add_u32 s100, s100, 0x1000
	s_addc_u32 s101, s101, 0
	global_load_ushort v82, v2, s[98:99]
	global_load_dword v90, v3, s[100:101]
	s_add_u32 s98, s98, 0x40000
	s_addc_u32 s99, s99, 0
	s_add_u32 s100, s100, 0x1000
	s_addc_u32 s101, s101, 0
	global_load_ushort v83, v2, s[98:99]
	global_load_dword v91, v3, s[100:101]
	s_add_u32 s98, s98, 0x40000
	s_addc_u32 s99, s99, 0
	s_add_u32 s100, s100, 0x1000
	s_addc_u32 s101, s101, 0
	s_waitcnt vmcnt(48)
; DI u16 f2bf(float x) { return (u16)(pack2(x, 0.f) & 0xffffu); }
; DI float bf2f(u16 h) { return __uint_as_float(((unsigned)h) << 16); }
; DI void hgrn_scan_phase(const Params& p, char* smem) {
;     ...
;     for (int n0 = 0; n0 < 256; n0 += 8) {
;       float nu[8], nd[8];
;       if (n0 + 8 < 256) {
; #pragma unroll
;         for (int j = 0; j < 8; j++) { nu[j] = bf2f(up[(long)(n0 + 8 + j) * 131072]); nd[j] = dp[(n0 + 8 + j) * 1024]; }
;       } else {
; #pragma unroll
;         for (int j = 0; j < 8; j++) { nu[j] = 0.f; nd[j] = 0.f; }
;       }
; #pragma unroll
;       for (int j = 0; j < 8; j++) { up[(long)(n0 + j) * 131072] = f2bf(S); S = cd[j] * S + cu[j]; }
; #pragma unroll
;       for (int j = 0; j < 8; j++) { cu[j] = nu[j]; cd[j] = nd[j]; }
;     }
	v_cvt_pk_bf16_f32 v50, v15, v15
	v_lshlrev_b32_e32 v54, 16, v92
	global_store_short v2, v50, s[40:41]
	v_fma_f32 v15, v100, v15, v54
	s_add_u32 s40, s40, 0x40000
	s_addc_u32 s41, s41, 0
	v_cvt_pk_bf16_f32 v51, v15, v15
	v_lshlrev_b32_e32 v54, 16, v93
	global_store_short v2, v51, s[40:41]
	v_fma_f32 v15, v101, v15, v54
	s_add_u32 s40, s40, 0x40000
	s_addc_u32 s41, s41, 0
	v_cvt_pk_bf16_f32 v52, v15, v15
	v_lshlrev_b32_e32 v54, 16, v94
	global_store_short v2, v52, s[40:41]
	v_fma_f32 v15, v102, v15, v54
	s_add_u32 s40, s40, 0x40000
	s_addc_u32 s41, s41, 0
	v_cvt_pk_bf16_f32 v53, v15, v15
	v_lshlrev_b32_e32 v54, 16, v95
	global_store_short v2, v53, s[40:41]
	v_fma_f32 v15, v103, v15, v54
	s_add_u32 s40, s40, 0x40000
	s_addc_u32 s41, s41, 0
	v_cvt_pk_bf16_f32 v50, v15, v15
	v_lshlrev_b32_e32 v54, 16, v96
	global_store_short v2, v50, s[40:41]
	v_fma_f32 v15, v104, v15, v54
	s_add_u32 s40, s40, 0x40000
	s_addc_u32 s41, s41, 0
	v_cvt_pk_bf16_f32 v51, v15, v15
	v_lshlrev_b32_e32 v54, 16, v97
	global_store_short v2, v51, s[40:41]
	v_fma_f32 v15, v105, v15, v54
	s_add_u32 s40, s40, 0x40000
	s_addc_u32 s41, s41, 0
	v_cvt_pk_bf16_f32 v52, v15, v15
	v_lshlrev_b32_e32 v54, 16, v98
	global_store_short v2, v52, s[40:41]
	v_fma_f32 v15, v106, v15, v54
	s_add_u32 s40, s40, 0x40000
	s_addc_u32 s41, s41, 0
	v_cvt_pk_bf16_f32 v53, v15, v15
	v_lshlrev_b32_e32 v54, 16, v99
	global_store_short v2, v53, s[40:41]
	v_fma_f32 v15, v107, v15, v54
	s_add_u32 s40, s40, 0x40000
	s_addc_u32 s41, s41, 0
	global_load_ushort v92, v2, s[98:99]
	global_load_dword v100, v3, s[100:101]
	s_add_u32 s98, s98, 0x40000
	s_addc_u32 s99, s99, 0
	s_add_u32 s100, s100, 0x1000
	s_addc_u32 s101, s101, 0
	global_load_ushort v93, v2, s[98:99]
	global_load_dword v101, v3, s[100:101]
	s_add_u32 s98, s98, 0x40000
	s_addc_u32 s99, s99, 0
	s_add_u32 s100, s100, 0x1000
	s_addc_u32 s101, s101, 0
	global_load_ushort v94, v2, s[98:99]
	global_load_dword v102, v3, s[100:101]
	s_add_u32 s98, s98, 0x40000
	s_addc_u32 s99, s99, 0
	s_add_u32 s100, s100, 0x1000
	s_addc_u32 s101, s101, 0
	global_load_ushort v95, v2, s[98:99]
	global_load_dword v103, v3, s[100:101]
	s_add_u32 s98, s98, 0x40000
	s_addc_u32 s99, s99, 0
	s_add_u32 s100, s100, 0x1000
	s_addc_u32 s101, s101, 0
	global_load_ushort v96, v2, s[98:99]
	global_load_dword v104, v3, s[100:101]
	s_add_u32 s98, s98, 0x40000
	s_addc_u32 s99, s99, 0
	s_add_u32 s100, s100, 0x1000
	s_addc_u32 s101, s101, 0
	global_load_ushort v97, v2, s[98:99]
	global_load_dword v105, v3, s[100:101]
	s_add_u32 s98, s98, 0x40000
	s_addc_u32 s99, s99, 0
	s_add_u32 s100, s100, 0x1000
	s_addc_u32 s101, s101, 0
	global_load_ushort v98, v2, s[98:99]
	global_load_dword v106, v3, s[100:101]
	s_add_u32 s98, s98, 0x40000
	s_addc_u32 s99, s99, 0
	s_add_u32 s100, s100, 0x1000
	s_addc_u32 s101, s101, 0
	global_load_ushort v99, v2, s[98:99]
	global_load_dword v107, v3, s[100:101]
	s_add_u32 s98, s98, 0x40000
	s_addc_u32 s99, s99, 0
	s_add_u32 s100, s100, 0x1000
	s_addc_u32 s101, s101, 0
	s_waitcnt vmcnt(48)
	v_cvt_pk_bf16_f32 v50, v15, v15
	v_lshlrev_b32_e32 v54, 16, v60
	global_store_short v2, v50, s[40:41]
	v_fma_f32 v15, v68, v15, v54
	s_add_u32 s40, s40, 0x40000
	s_addc_u32 s41, s41, 0
	v_cvt_pk_bf16_f32 v51, v15, v15
	v_lshlrev_b32_e32 v54, 16, v61
	global_store_short v2, v51, s[40:41]
	v_fma_f32 v15, v69, v15, v54
	s_add_u32 s40, s40, 0x40000
	s_addc_u32 s41, s41, 0
	v_cvt_pk_bf16_f32 v52, v15, v15
	v_lshlrev_b32_e32 v54, 16, v62
	global_store_short v2, v52, s[40:41]
	v_fma_f32 v15, v70, v15, v54
	s_add_u32 s40, s40, 0x40000
	s_addc_u32 s41, s41, 0
	v_cvt_pk_bf16_f32 v53, v15, v15
	v_lshlrev_b32_e32 v54, 16, v63
	global_store_short v2, v53, s[40:41]
	v_fma_f32 v15, v71, v15, v54
	s_add_u32 s40, s40, 0x40000
	s_addc_u32 s41, s41, 0
	v_cvt_pk_bf16_f32 v50, v15, v15
	v_lshlrev_b32_e32 v54, 16, v64
	global_store_short v2, v50, s[40:41]
	v_fma_f32 v15, v72, v15, v54
	s_add_u32 s40, s40, 0x40000
	s_addc_u32 s41, s41, 0
	v_cvt_pk_bf16_f32 v51, v15, v15
	v_lshlrev_b32_e32 v54, 16, v65
	global_store_short v2, v51, s[40:41]
	v_fma_f32 v15, v73, v15, v54
	s_add_u32 s40, s40, 0x40000
	s_addc_u32 s41, s41, 0
	v_cvt_pk_bf16_f32 v52, v15, v15
	v_lshlrev_b32_e32 v54, 16, v66
	global_store_short v2, v52, s[40:41]
	v_fma_f32 v15, v74, v15, v54
	s_add_u32 s40, s40, 0x40000
	s_addc_u32 s41, s41, 0
	v_cvt_pk_bf16_f32 v53, v15, v15
	v_lshlrev_b32_e32 v54, 16, v67
	global_store_short v2, v53, s[40:41]
	v_fma_f32 v15, v75, v15, v54
	s_add_u32 s40, s40, 0x40000
	s_addc_u32 s41, s41, 0
	global_load_ushort v60, v2, s[98:99]
	global_load_dword v68, v3, s[100:101]
	s_add_u32 s98, s98, 0x40000
	s_addc_u32 s99, s99, 0
	s_add_u32 s100, s100, 0x1000
	s_addc_u32 s101, s101, 0
	global_load_ushort v61, v2, s[98:99]
	global_load_dword v69, v3, s[100:101]
	s_add_u32 s98, s98, 0x40000
	s_addc_u32 s99, s99, 0
	s_add_u32 s100, s100, 0x1000
	s_addc_u32 s101, s101, 0
	global_load_ushort v62, v2, s[98:99]
	global_load_dword v70, v3, s[100:101]
	s_add_u32 s98, s98, 0x40000
	s_addc_u32 s99, s99, 0
	s_add_u32 s100, s100, 0x1000
	s_addc_u32 s101, s101, 0
	global_load_ushort v63, v2, s[98:99]
	global_load_dword v71, v3, s[100:101]
	s_add_u32 s98, s98, 0x40000
	s_addc_u32 s99, s99, 0
	s_add_u32 s100, s100, 0x1000
	s_addc_u32 s101, s101, 0
	global_load_ushort v64, v2, s[98:99]
	global_load_dword v72, v3, s[100:101]
	s_add_u32 s98, s98, 0x40000
	s_addc_u32 s99, s99, 0
	s_add_u32 s100, s100, 0x1000
	s_addc_u32 s101, s101, 0
	global_load_ushort v65, v2, s[98:99]
	global_load_dword v73, v3, s[100:101]
	s_add_u32 s98, s98, 0x40000
	s_addc_u32 s99, s99, 0
	s_add_u32 s100, s100, 0x1000
	s_addc_u32 s101, s101, 0
	global_load_ushort v66, v2, s[98:99]
	global_load_dword v74, v3, s[100:101]
	s_add_u32 s98, s98, 0x40000
	s_addc_u32 s99, s99, 0
	s_add_u32 s100, s100, 0x1000
	s_addc_u32 s101, s101, 0
	global_load_ushort v67, v2, s[98:99]
	global_load_dword v75, v3, s[100:101]
	s_add_u32 s98, s98, 0x40000
	s_addc_u32 s99, s99, 0
	s_add_u32 s100, s100, 0x1000
	s_addc_u32 s101, s101, 0
	s_waitcnt vmcnt(48)
; DI u16 f2bf(float x) { return (u16)(pack2(x, 0.f) & 0xffffu); }
; DI float bf2f(u16 h) { return __uint_as_float(((unsigned)h) << 16); }
; DI void hgrn_scan_phase(const Params& p, char* smem) {
;     ...
;     for (int n0 = 0; n0 < 256; n0 += 8) {
;       float nu[8], nd[8];
;       if (n0 + 8 < 256) {
; #pragma unroll
;         for (int j = 0; j < 8; j++) { nu[j] = bf2f(up[(long)(n0 + 8 + j) * 131072]); nd[j] = dp[(n0 + 8 + j) * 1024]; }
;       } else {
; #pragma unroll
;         for (int j = 0; j < 8; j++) { nu[j] = 0.f; nd[j] = 0.f; }
;       }
; #pragma unroll
;       for (int j = 0; j < 8; j++) { up[(long)(n0 + j) * 131072] = f2bf(S); S = cd[j] * S + cu[j]; }
; #pragma unroll
;       for (int j = 0; j < 8; j++) { cu[j] = nu[j]; cd[j] = nd[j]; }
;     }
	v_cvt_pk_bf16_f32 v50, v15, v15
	v_lshlrev_b32_e32 v54, 16, v76
	global_store_short v2, v50, s[40:41]
	v_fma_f32 v15, v84, v15, v54
	s_add_u32 s40, s40, 0x40000
	s_addc_u32 s41, s41, 0
	v_cvt_pk_bf16_f32 v51, v15, v15
	v_lshlrev_b32_e32 v54, 16, v77
	global_store_short v2, v51, s[40:41]
	v_fma_f32 v15, v85, v15, v54
	s_add_u32 s40, s40, 0x40000
	s_addc_u32 s41, s41, 0
	v_cvt_pk_bf16_f32 v52, v15, v15
	v_lshlrev_b32_e32 v54, 16, v78
	global_store_short v2, v52, s[40:41]
	v_fma_f32 v15, v86, v15, v54
	s_add_u32 s40, s40, 0x40000
	s_addc_u32 s41, s41, 0
	v_cvt_pk_bf16_f32 v53, v15, v15
	v_lshlrev_b32_e32 v54, 16, v79
	global_store_short v2, v53, s[40:41]
	v_fma_f32 v15, v87, v15, v54
	s_add_u32 s40, s40, 0x40000
	s_addc_u32 s41, s41, 0
	v_cvt_pk_bf16_f32 v50, v15, v15
	v_lshlrev_b32_e32 v54, 16, v80
	global_store_short v2, v50, s[40:41]
	v_fma_f32 v15, v88, v15, v54
	s_add_u32 s40, s40, 0x40000
	s_addc_u32 s41, s41, 0
	v_cvt_pk_bf16_f32 v51, v15, v15
	v_lshlrev_b32_e32 v54, 16, v81
	global_store_short v2, v51, s[40:41]
	v_fma_f32 v15, v89, v15, v54
	s_add_u32 s40, s40, 0x40000
	s_addc_u32 s41, s41, 0
	v_cvt_pk_bf16_f32 v52, v15, v15
	v_lshlrev_b32_e32 v54, 16, v82
	global_store_short v2, v52, s[40:41]
	v_fma_f32 v15, v90, v15, v54
	s_add_u32 s40, s40, 0x40000
	s_addc_u32 s41, s41, 0
	v_cvt_pk_bf16_f32 v53, v15, v15
	v_lshlrev_b32_e32 v54, 16, v83
	global_store_short v2, v53, s[40:41]
	v_fma_f32 v15, v91, v15, v54
	s_add_u32 s40, s40, 0x40000
	s_addc_u32 s41, s41, 0
	global_load_ushort v76, v2, s[98:99]
	global_load_dword v84, v3, s[100:101]
	s_add_u32 s98, s98, 0x40000
	s_addc_u32 s99, s99, 0
	s_add_u32 s100, s100, 0x1000
	s_addc_u32 s101, s101, 0
	global_load_ushort v77, v2, s[98:99]
	global_load_dword v85, v3, s[100:101]
	s_add_u32 s98, s98, 0x40000
	s_addc_u32 s99, s99, 0
	s_add_u32 s100, s100, 0x1000
	s_addc_u32 s101, s101, 0
	global_load_ushort v78, v2, s[98:99]
	global_load_dword v86, v3, s[100:101]
	s_add_u32 s98, s98, 0x40000
	s_addc_u32 s99, s99, 0
	s_add_u32 s100, s100, 0x1000
	s_addc_u32 s101, s101, 0
	global_load_ushort v79, v2, s[98:99]
	global_load_dword v87, v3, s[100:101]
	s_add_u32 s98, s98, 0x40000
	s_addc_u32 s99, s99, 0
	s_add_u32 s100, s100, 0x1000
	s_addc_u32 s101, s101, 0
	global_load_ushort v80, v2, s[98:99]
	global_load_dword v88, v3, s[100:101]
	s_add_u32 s98, s98, 0x40000
	s_addc_u32 s99, s99, 0
	s_add_u32 s100, s100, 0x1000
	s_addc_u32 s101, s101, 0
	global_load_ushort v81, v2, s[98:99]
	global_load_dword v89, v3, s[100:101]
	s_add_u32 s98, s98, 0x40000
	s_addc_u32 s99, s99, 0
	s_add_u32 s100, s100, 0x1000
	s_addc_u32 s101, s101, 0
	global_load_ushort v82, v2, s[98:99]
	global_load_dword v90, v3, s[100:101]
	s_add_u32 s98, s98, 0x40000
	s_addc_u32 s99, s99, 0
	s_add_u32 s100, s100, 0x1000
	s_addc_u32 s101, s101, 0
	global_load_ushort v83, v2, s[98:99]
	global_load_dword v91, v3, s[100:101]
	s_add_u32 s98, s98, 0x40000
	s_addc_u32 s99, s99, 0
	s_add_u32 s100, s100, 0x1000
	s_addc_u32 s101, s101, 0
	s_waitcnt vmcnt(48)
	v_cvt_pk_bf16_f32 v50, v15, v15
	v_lshlrev_b32_e32 v54, 16, v92
	global_store_short v2, v50, s[40:41]
	v_fma_f32 v15, v100, v15, v54
	s_add_u32 s40, s40, 0x40000
	s_addc_u32 s41, s41, 0
	v_cvt_pk_bf16_f32 v51, v15, v15
	v_lshlrev_b32_e32 v54, 16, v93
	global_store_short v2, v51, s[40:41]
	v_fma_f32 v15, v101, v15, v54
	s_add_u32 s40, s40, 0x40000
	s_addc_u32 s41, s41, 0
	v_cvt_pk_bf16_f32 v52, v15, v15
	v_lshlrev_b32_e32 v54, 16, v94
	global_store_short v2, v52, s[40:41]
	v_fma_f32 v15, v102, v15, v54
	s_add_u32 s40, s40, 0x40000
	s_addc_u32 s41, s41, 0
	v_cvt_pk_bf16_f32 v53, v15, v15
	v_lshlrev_b32_e32 v54, 16, v95
	global_store_short v2, v53, s[40:41]
	v_fma_f32 v15, v103, v15, v54
	s_add_u32 s40, s40, 0x40000
	s_addc_u32 s41, s41, 0
	v_cvt_pk_bf16_f32 v50, v15, v15
	v_lshlrev_b32_e32 v54, 16, v96
	global_store_short v2, v50, s[40:41]
	v_fma_f32 v15, v104, v15, v54
	s_add_u32 s40, s40, 0x40000
	s_addc_u32 s41, s41, 0
	v_cvt_pk_bf16_f32 v51, v15, v15
	v_lshlrev_b32_e32 v54, 16, v97
	global_store_short v2, v51, s[40:41]
	v_fma_f32 v15, v105, v15, v54
	s_add_u32 s40, s40, 0x40000
	s_addc_u32 s41, s41, 0
	v_cvt_pk_bf16_f32 v52, v15, v15
	v_lshlrev_b32_e32 v54, 16, v98
	global_store_short v2, v52, s[40:41]
	v_fma_f32 v15, v106, v15, v54
	s_add_u32 s40, s40, 0x40000
	s_addc_u32 s41, s41, 0
	v_cvt_pk_bf16_f32 v53, v15, v15
	v_lshlrev_b32_e32 v54, 16, v99
	global_store_short v2, v53, s[40:41]
	v_fma_f32 v15, v107, v15, v54
	s_add_u32 s40, s40, 0x40000
	s_addc_u32 s41, s41, 0
	global_load_ushort v92, v2, s[98:99]
	global_load_dword v100, v3, s[100:101]
	s_add_u32 s98, s98, 0x40000
	s_addc_u32 s99, s99, 0
	s_add_u32 s100, s100, 0x1000
	s_addc_u32 s101, s101, 0
	global_load_ushort v93, v2, s[98:99]
	global_load_dword v101, v3, s[100:101]
	s_add_u32 s98, s98, 0x40000
	s_addc_u32 s99, s99, 0
	s_add_u32 s100, s100, 0x1000
	s_addc_u32 s101, s101, 0
	global_load_ushort v94, v2, s[98:99]
	global_load_dword v102, v3, s[100:101]
	s_add_u32 s98, s98, 0x40000
	s_addc_u32 s99, s99, 0
	s_add_u32 s100, s100, 0x1000
	s_addc_u32 s101, s101, 0
	global_load_ushort v95, v2, s[98:99]
	global_load_dword v103, v3, s[100:101]
	s_add_u32 s98, s98, 0x40000
	s_addc_u32 s99, s99, 0
	s_add_u32 s100, s100, 0x1000
	s_addc_u32 s101, s101, 0
	global_load_ushort v96, v2, s[98:99]
	global_load_dword v104, v3, s[100:101]
	s_add_u32 s98, s98, 0x40000
	s_addc_u32 s99, s99, 0
	s_add_u32 s100, s100, 0x1000
	s_addc_u32 s101, s101, 0
	global_load_ushort v97, v2, s[98:99]
	global_load_dword v105, v3, s[100:101]
	s_add_u32 s98, s98, 0x40000
	s_addc_u32 s99, s99, 0
	s_add_u32 s100, s100, 0x1000
	s_addc_u32 s101, s101, 0
	global_load_ushort v98, v2, s[98:99]
	global_load_dword v106, v3, s[100:101]
	s_add_u32 s98, s98, 0x40000
	s_addc_u32 s99, s99, 0
	s_add_u32 s100, s100, 0x1000
	s_addc_u32 s101, s101, 0
	global_load_ushort v99, v2, s[98:99]
	global_load_dword v107, v3, s[100:101]
	s_add_u32 s98, s98, 0x40000
	s_addc_u32 s99, s99, 0
	s_add_u32 s100, s100, 0x1000
	s_addc_u32 s101, s101, 0
	s_waitcnt vmcnt(48)
; DI u16 f2bf(float x) { return (u16)(pack2(x, 0.f) & 0xffffu); }
; DI float bf2f(u16 h) { return __uint_as_float(((unsigned)h) << 16); }
; DI void hgrn_scan_phase(const Params& p, char* smem) {
;     ...
;     for (int n0 = 0; n0 < 256; n0 += 8) {
;       float nu[8], nd[8];
;       if (n0 + 8 < 256) {
; #pragma unroll
;         for (int j = 0; j < 8; j++) { nu[j] = bf2f(up[(long)(n0 + 8 + j) * 131072]); nd[j] = dp[(n0 + 8 + j) * 1024]; }
;       } else {
; #pragma unroll
;         for (int j = 0; j < 8; j++) { nu[j] = 0.f; nd[j] = 0.f; }
;       }
; #pragma unroll
;       for (int j = 0; j < 8; j++) { up[(long)(n0 + j) * 131072] = f2bf(S); S = cd[j] * S + cu[j]; }
; #pragma unroll
;       for (int j = 0; j < 8; j++) { cu[j] = nu[j]; cd[j] = nd[j]; }
;     }
	v_cvt_pk_bf16_f32 v50, v15, v15
	v_lshlrev_b32_e32 v54, 16, v60
	global_store_short v2, v50, s[40:41]
	v_fma_f32 v15, v68, v15, v54
	s_add_u32 s40, s40, 0x40000
	s_addc_u32 s41, s41, 0
	v_cvt_pk_bf16_f32 v51, v15, v15
	v_lshlrev_b32_e32 v54, 16, v61
	global_store_short v2, v51, s[40:41]
	v_fma_f32 v15, v69, v15, v54
	s_add_u32 s40, s40, 0x40000
	s_addc_u32 s41, s41, 0
	v_cvt_pk_bf16_f32 v52, v15, v15
	v_lshlrev_b32_e32 v54, 16, v62
	global_store_short v2, v52, s[40:41]
	v_fma_f32 v15, v70, v15, v54
	s_add_u32 s40, s40, 0x40000
	s_addc_u32 s41, s41, 0
	v_cvt_pk_bf16_f32 v53, v15, v15
	v_lshlrev_b32_e32 v54, 16, v63
	global_store_short v2, v53, s[40:41]
	v_fma_f32 v15, v71, v15, v54
	s_add_u32 s40, s40, 0x40000
	s_addc_u32 s41, s41, 0
	v_cvt_pk_bf16_f32 v50, v15, v15
	v_lshlrev_b32_e32 v54, 16, v64
	global_store_short v2, v50, s[40:41]
	v_fma_f32 v15, v72, v15, v54
	s_add_u32 s40, s40, 0x40000
	s_addc_u32 s41, s41, 0
	v_cvt_pk_bf16_f32 v51, v15, v15
	v_lshlrev_b32_e32 v54, 16, v65
	global_store_short v2, v51, s[40:41]
	v_fma_f32 v15, v73, v15, v54
	s_add_u32 s40, s40, 0x40000
	s_addc_u32 s41, s41, 0
	v_cvt_pk_bf16_f32 v52, v15, v15
	v_lshlrev_b32_e32 v54, 16, v66
	global_store_short v2, v52, s[40:41]
	v_fma_f32 v15, v74, v15, v54
	s_add_u32 s40, s40, 0x40000
	s_addc_u32 s41, s41, 0
	v_cvt_pk_bf16_f32 v53, v15, v15
	v_lshlrev_b32_e32 v54, 16, v67
	global_store_short v2, v53, s[40:41]
	v_fma_f32 v15, v75, v15, v54
	s_add_u32 s40, s40, 0x40000
	s_addc_u32 s41, s41, 0
	global_load_ushort v60, v2, s[98:99]
	global_load_dword v68, v3, s[100:101]
	s_add_u32 s98, s98, 0x40000
	s_addc_u32 s99, s99, 0
	s_add_u32 s100, s100, 0x1000
	s_addc_u32 s101, s101, 0
	global_load_ushort v61, v2, s[98:99]
	global_load_dword v69, v3, s[100:101]
	s_add_u32 s98, s98, 0x40000
	s_addc_u32 s99, s99, 0
	s_add_u32 s100, s100, 0x1000
	s_addc_u32 s101, s101, 0
	global_load_ushort v62, v2, s[98:99]
	global_load_dword v70, v3, s[100:101]
	s_add_u32 s98, s98, 0x40000
	s_addc_u32 s99, s99, 0
	s_add_u32 s100, s100, 0x1000
	s_addc_u32 s101, s101, 0
	global_load_ushort v63, v2, s[98:99]
	global_load_dword v71, v3, s[100:101]
	s_add_u32 s98, s98, 0x40000
	s_addc_u32 s99, s99, 0
	s_add_u32 s100, s100, 0x1000
	s_addc_u32 s101, s101, 0
	global_load_ushort v64, v2, s[98:99]
	global_load_dword v72, v3, s[100:101]
	s_add_u32 s98, s98, 0x40000
	s_addc_u32 s99, s99, 0
	s_add_u32 s100, s100, 0x1000
	s_addc_u32 s101, s101, 0
	global_load_ushort v65, v2, s[98:99]
	global_load_dword v73, v3, s[100:101]
	s_add_u32 s98, s98, 0x40000
	s_addc_u32 s99, s99, 0
	s_add_u32 s100, s100, 0x1000
	s_addc_u32 s101, s101, 0
	global_load_ushort v66, v2, s[98:99]
	global_load_dword v74, v3, s[100:101]
	s_add_u32 s98, s98, 0x40000
	s_addc_u32 s99, s99, 0
	s_add_u32 s100, s100, 0x1000
	s_addc_u32 s101, s101, 0
	global_load_ushort v67, v2, s[98:99]
	global_load_dword v75, v3, s[100:101]
	s_add_u32 s98, s98, 0x40000
	s_addc_u32 s99, s99, 0
	s_add_u32 s100, s100, 0x1000
	s_addc_u32 s101, s101, 0
	s_waitcnt vmcnt(48)
	v_cvt_pk_bf16_f32 v50, v15, v15
	v_lshlrev_b32_e32 v54, 16, v76
	global_store_short v2, v50, s[40:41]
	v_fma_f32 v15, v84, v15, v54
	s_add_u32 s40, s40, 0x40000
	s_addc_u32 s41, s41, 0
	v_cvt_pk_bf16_f32 v51, v15, v15
	v_lshlrev_b32_e32 v54, 16, v77
	global_store_short v2, v51, s[40:41]
	v_fma_f32 v15, v85, v15, v54
	s_add_u32 s40, s40, 0x40000
	s_addc_u32 s41, s41, 0
	v_cvt_pk_bf16_f32 v52, v15, v15
	v_lshlrev_b32_e32 v54, 16, v78
	global_store_short v2, v52, s[40:41]
	v_fma_f32 v15, v86, v15, v54
	s_add_u32 s40, s40, 0x40000
	s_addc_u32 s41, s41, 0
	v_cvt_pk_bf16_f32 v53, v15, v15
	v_lshlrev_b32_e32 v54, 16, v79
	global_store_short v2, v53, s[40:41]
	v_fma_f32 v15, v87, v15, v54
	s_add_u32 s40, s40, 0x40000
	s_addc_u32 s41, s41, 0
	v_cvt_pk_bf16_f32 v50, v15, v15
	v_lshlrev_b32_e32 v54, 16, v80
	global_store_short v2, v50, s[40:41]
	v_fma_f32 v15, v88, v15, v54
	s_add_u32 s40, s40, 0x40000
	s_addc_u32 s41, s41, 0
	v_cvt_pk_bf16_f32 v51, v15, v15
	v_lshlrev_b32_e32 v54, 16, v81
	global_store_short v2, v51, s[40:41]
	v_fma_f32 v15, v89, v15, v54
	s_add_u32 s40, s40, 0x40000
	s_addc_u32 s41, s41, 0
	v_cvt_pk_bf16_f32 v52, v15, v15
	v_lshlrev_b32_e32 v54, 16, v82
	global_store_short v2, v52, s[40:41]
	v_fma_f32 v15, v90, v15, v54
	s_add_u32 s40, s40, 0x40000
	s_addc_u32 s41, s41, 0
	v_cvt_pk_bf16_f32 v53, v15, v15
	v_lshlrev_b32_e32 v54, 16, v83
	global_store_short v2, v53, s[40:41]
	v_fma_f32 v15, v91, v15, v54
	s_add_u32 s40, s40, 0x40000
	s_addc_u32 s41, s41, 0
	global_load_ushort v76, v2, s[98:99]
	global_load_dword v84, v3, s[100:101]
	s_add_u32 s98, s98, 0x40000
	s_addc_u32 s99, s99, 0
	s_add_u32 s100, s100, 0x1000
	s_addc_u32 s101, s101, 0
	global_load_ushort v77, v2, s[98:99]
	global_load_dword v85, v3, s[100:101]
	s_add_u32 s98, s98, 0x40000
	s_addc_u32 s99, s99, 0
	s_add_u32 s100, s100, 0x1000
	s_addc_u32 s101, s101, 0
	global_load_ushort v78, v2, s[98:99]
	global_load_dword v86, v3, s[100:101]
	s_add_u32 s98, s98, 0x40000
	s_addc_u32 s99, s99, 0
	s_add_u32 s100, s100, 0x1000
	s_addc_u32 s101, s101, 0
	global_load_ushort v79, v2, s[98:99]
	global_load_dword v87, v3, s[100:101]
	s_add_u32 s98, s98, 0x40000
	s_addc_u32 s99, s99, 0
	s_add_u32 s100, s100, 0x1000
	s_addc_u32 s101, s101, 0
	global_load_ushort v80, v2, s[98:99]
	global_load_dword v88, v3, s[100:101]
	s_add_u32 s98, s98, 0x40000
	s_addc_u32 s99, s99, 0
	s_add_u32 s100, s100, 0x1000
	s_addc_u32 s101, s101, 0
	global_load_ushort v81, v2, s[98:99]
	global_load_dword v89, v3, s[100:101]
	s_add_u32 s98, s98, 0x40000
	s_addc_u32 s99, s99, 0
	s_add_u32 s100, s100, 0x1000
	s_addc_u32 s101, s101, 0
	global_load_ushort v82, v2, s[98:99]
	global_load_dword v90, v3, s[100:101]
	s_add_u32 s98, s98, 0x40000
	s_addc_u32 s99, s99, 0
	s_add_u32 s100, s100, 0x1000
	s_addc_u32 s101, s101, 0
	global_load_ushort v83, v2, s[98:99]
	global_load_dword v91, v3, s[100:101]
	s_add_u32 s98, s98, 0x40000
	s_addc_u32 s99, s99, 0
	s_add_u32 s100, s100, 0x1000
	s_addc_u32 s101, s101, 0
	s_waitcnt vmcnt(48)
; DI u16 f2bf(float x) { return (u16)(pack2(x, 0.f) & 0xffffu); }
; DI float bf2f(u16 h) { return __uint_as_float(((unsigned)h) << 16); }
; DI void hgrn_scan_phase(const Params& p, char* smem) {
;     ...
;     for (int n0 = 0; n0 < 256; n0 += 8) {
;       float nu[8], nd[8];
;       if (n0 + 8 < 256) {
; #pragma unroll
;         for (int j = 0; j < 8; j++) { nu[j] = bf2f(up[(long)(n0 + 8 + j) * 131072]); nd[j] = dp[(n0 + 8 + j) * 1024]; }
;       } else {
; #pragma unroll
;         for (int j = 0; j < 8; j++) { nu[j] = 0.f; nd[j] = 0.f; }
;       }
; #pragma unroll
;       for (int j = 0; j < 8; j++) { up[(long)(n0 + j) * 131072] = f2bf(S); S = cd[j] * S + cu[j]; }
; #pragma unroll
;       for (int j = 0; j < 8; j++) { cu[j] = nu[j]; cd[j] = nd[j]; }
;     }
	v_cvt_pk_bf16_f32 v50, v15, v15
	v_lshlrev_b32_e32 v54, 16, v92
	global_store_short v2, v50, s[40:41]
	v_fma_f32 v15, v100, v15, v54
	s_add_u32 s40, s40, 0x40000
	s_addc_u32 s41, s41, 0
	v_cvt_pk_bf16_f32 v51, v15, v15
	v_lshlrev_b32_e32 v54, 16, v93
	global_store_short v2, v51, s[40:41]
	v_fma_f32 v15, v101, v15, v54
	s_add_u32 s40, s40, 0x40000
	s_addc_u32 s41, s41, 0
	v_cvt_pk_bf16_f32 v52, v15, v15
	v_lshlrev_b32_e32 v54, 16, v94
	global_store_short v2, v52, s[40:41]
	v_fma_f32 v15, v102, v15, v54
	s_add_u32 s40, s40, 0x40000
	s_addc_u32 s41, s41, 0
	v_cvt_pk_bf16_f32 v53, v15, v15
	v_lshlrev_b32_e32 v54, 16, v95
	global_store_short v2, v53, s[40:41]
	v_fma_f32 v15, v103, v15, v54
	s_add_u32 s40, s40, 0x40000
	s_addc_u32 s41, s41, 0
	v_cvt_pk_bf16_f32 v50, v15, v15
	v_lshlrev_b32_e32 v54, 16, v96
	global_store_short v2, v50, s[40:41]
	v_fma_f32 v15, v104, v15, v54
	s_add_u32 s40, s40, 0x40000
	s_addc_u32 s41, s41, 0
	v_cvt_pk_bf16_f32 v51, v15, v15
	v_lshlrev_b32_e32 v54, 16, v97
	global_store_short v2, v51, s[40:41]
	v_fma_f32 v15, v105, v15, v54
	s_add_u32 s40, s40, 0x40000
	s_addc_u32 s41, s41, 0
	v_cvt_pk_bf16_f32 v52, v15, v15
	v_lshlrev_b32_e32 v54, 16, v98
	global_store_short v2, v52, s[40:41]
	v_fma_f32 v15, v106, v15, v54
	s_add_u32 s40, s40, 0x40000
	s_addc_u32 s41, s41, 0
	v_cvt_pk_bf16_f32 v53, v15, v15
	v_lshlrev_b32_e32 v54, 16, v99
	global_store_short v2, v53, s[40:41]
	v_fma_f32 v15, v107, v15, v54
	s_add_u32 s40, s40, 0x40000
	s_addc_u32 s41, s41, 0
	global_load_ushort v92, v2, s[98:99]
	global_load_dword v100, v3, s[100:101]
	s_add_u32 s98, s98, 0x40000
	s_addc_u32 s99, s99, 0
	s_add_u32 s100, s100, 0x1000
	s_addc_u32 s101, s101, 0
	global_load_ushort v93, v2, s[98:99]
	global_load_dword v101, v3, s[100:101]
	s_add_u32 s98, s98, 0x40000
	s_addc_u32 s99, s99, 0
	s_add_u32 s100, s100, 0x1000
	s_addc_u32 s101, s101, 0
	global_load_ushort v94, v2, s[98:99]
	global_load_dword v102, v3, s[100:101]
	s_add_u32 s98, s98, 0x40000
	s_addc_u32 s99, s99, 0
	s_add_u32 s100, s100, 0x1000
	s_addc_u32 s101, s101, 0
	global_load_ushort v95, v2, s[98:99]
	global_load_dword v103, v3, s[100:101]
	s_add_u32 s98, s98, 0x40000
	s_addc_u32 s99, s99, 0
	s_add_u32 s100, s100, 0x1000
	s_addc_u32 s101, s101, 0
	global_load_ushort v96, v2, s[98:99]
	global_load_dword v104, v3, s[100:101]
	s_add_u32 s98, s98, 0x40000
	s_addc_u32 s99, s99, 0
	s_add_u32 s100, s100, 0x1000
	s_addc_u32 s101, s101, 0
	global_load_ushort v97, v2, s[98:99]
	global_load_dword v105, v3, s[100:101]
	s_add_u32 s98, s98, 0x40000
	s_addc_u32 s99, s99, 0
	s_add_u32 s100, s100, 0x1000
	s_addc_u32 s101, s101, 0
	global_load_ushort v98, v2, s[98:99]
	global_load_dword v106, v3, s[100:101]
	s_add_u32 s98, s98, 0x40000
	s_addc_u32 s99, s99, 0
	s_add_u32 s100, s100, 0x1000
	s_addc_u32 s101, s101, 0
	global_load_ushort v99, v2, s[98:99]
	global_load_dword v107, v3, s[100:101]
	s_add_u32 s98, s98, 0x40000
	s_addc_u32 s99, s99, 0
	s_add_u32 s100, s100, 0x1000
	s_addc_u32 s101, s101, 0
	s_waitcnt vmcnt(48)
	v_cvt_pk_bf16_f32 v50, v15, v15
	v_lshlrev_b32_e32 v54, 16, v60
	global_store_short v2, v50, s[40:41]
	v_fma_f32 v15, v68, v15, v54
	s_add_u32 s40, s40, 0x40000
	s_addc_u32 s41, s41, 0
	v_cvt_pk_bf16_f32 v51, v15, v15
	v_lshlrev_b32_e32 v54, 16, v61
	global_store_short v2, v51, s[40:41]
	v_fma_f32 v15, v69, v15, v54
	s_add_u32 s40, s40, 0x40000
	s_addc_u32 s41, s41, 0
	v_cvt_pk_bf16_f32 v52, v15, v15
	v_lshlrev_b32_e32 v54, 16, v62
	global_store_short v2, v52, s[40:41]
	v_fma_f32 v15, v70, v15, v54
	s_add_u32 s40, s40, 0x40000
	s_addc_u32 s41, s41, 0
	v_cvt_pk_bf16_f32 v53, v15, v15
	v_lshlrev_b32_e32 v54, 16, v63
	global_store_short v2, v53, s[40:41]
	v_fma_f32 v15, v71, v15, v54
	s_add_u32 s40, s40, 0x40000
	s_addc_u32 s41, s41, 0
	v_cvt_pk_bf16_f32 v50, v15, v15
	v_lshlrev_b32_e32 v54, 16, v64
	global_store_short v2, v50, s[40:41]
	v_fma_f32 v15, v72, v15, v54
	s_add_u32 s40, s40, 0x40000
	s_addc_u32 s41, s41, 0
	v_cvt_pk_bf16_f32 v51, v15, v15
	v_lshlrev_b32_e32 v54, 16, v65
	global_store_short v2, v51, s[40:41]
	v_fma_f32 v15, v73, v15, v54
	s_add_u32 s40, s40, 0x40000
	s_addc_u32 s41, s41, 0
	v_cvt_pk_bf16_f32 v52, v15, v15
	v_lshlrev_b32_e32 v54, 16, v66
	global_store_short v2, v52, s[40:41]
	v_fma_f32 v15, v74, v15, v54
	s_add_u32 s40, s40, 0x40000
	s_addc_u32 s41, s41, 0
	v_cvt_pk_bf16_f32 v53, v15, v15
	v_lshlrev_b32_e32 v54, 16, v67
	global_store_short v2, v53, s[40:41]
	v_fma_f32 v15, v75, v15, v54
	s_add_u32 s40, s40, 0x40000
	s_addc_u32 s41, s41, 0
	global_load_ushort v60, v2, s[98:99]
	global_load_dword v68, v3, s[100:101]
	s_add_u32 s98, s98, 0x40000
	s_addc_u32 s99, s99, 0
	s_add_u32 s100, s100, 0x1000
	s_addc_u32 s101, s101, 0
	global_load_ushort v61, v2, s[98:99]
	global_load_dword v69, v3, s[100:101]
	s_add_u32 s98, s98, 0x40000
	s_addc_u32 s99, s99, 0
	s_add_u32 s100, s100, 0x1000
	s_addc_u32 s101, s101, 0
	global_load_ushort v62, v2, s[98:99]
	global_load_dword v70, v3, s[100:101]
	s_add_u32 s98, s98, 0x40000
	s_addc_u32 s99, s99, 0
	s_add_u32 s100, s100, 0x1000
	s_addc_u32 s101, s101, 0
	global_load_ushort v63, v2, s[98:99]
	global_load_dword v71, v3, s[100:101]
	s_add_u32 s98, s98, 0x40000
	s_addc_u32 s99, s99, 0
	s_add_u32 s100, s100, 0x1000
	s_addc_u32 s101, s101, 0
	global_load_ushort v64, v2, s[98:99]
	global_load_dword v72, v3, s[100:101]
	s_add_u32 s98, s98, 0x40000
	s_addc_u32 s99, s99, 0
	s_add_u32 s100, s100, 0x1000
	s_addc_u32 s101, s101, 0
	global_load_ushort v65, v2, s[98:99]
	global_load_dword v73, v3, s[100:101]
	s_add_u32 s98, s98, 0x40000
	s_addc_u32 s99, s99, 0
	s_add_u32 s100, s100, 0x1000
	s_addc_u32 s101, s101, 0
	global_load_ushort v66, v2, s[98:99]
	global_load_dword v74, v3, s[100:101]
	s_add_u32 s98, s98, 0x40000
	s_addc_u32 s99, s99, 0
	s_add_u32 s100, s100, 0x1000
	s_addc_u32 s101, s101, 0
	global_load_ushort v67, v2, s[98:99]
	global_load_dword v75, v3, s[100:101]
	s_add_u32 s98, s98, 0x40000
	s_addc_u32 s99, s99, 0
	s_add_u32 s100, s100, 0x1000
	s_addc_u32 s101, s101, 0
	s_waitcnt vmcnt(48)
; DI u16 f2bf(float x) { return (u16)(pack2(x, 0.f) & 0xffffu); }
; DI float bf2f(u16 h) { return __uint_as_float(((unsigned)h) << 16); }
; DI void hgrn_scan_phase(const Params& p, char* smem) {
;     ...
;     for (int n0 = 0; n0 < 256; n0 += 8) {
;       float nu[8], nd[8];
;       if (n0 + 8 < 256) {
; #pragma unroll
;         for (int j = 0; j < 8; j++) { nu[j] = bf2f(up[(long)(n0 + 8 + j) * 131072]); nd[j] = dp[(n0 + 8 + j) * 1024]; }
;       } else {
; #pragma unroll
;         for (int j = 0; j < 8; j++) { nu[j] = 0.f; nd[j] = 0.f; }
;       }
; #pragma unroll
;       for (int j = 0; j < 8; j++) { up[(long)(n0 + j) * 131072] = f2bf(S); S = cd[j] * S + cu[j]; }
; #pragma unroll
;       for (int j = 0; j < 8; j++) { cu[j] = nu[j]; cd[j] = nd[j]; }
;     }
	v_cvt_pk_bf16_f32 v50, v15, v15
	v_lshlrev_b32_e32 v54, 16, v76
	global_store_short v2, v50, s[40:41]
	v_fma_f32 v15, v84, v15, v54
	s_add_u32 s40, s40, 0x40000
	s_addc_u32 s41, s41, 0
	v_cvt_pk_bf16_f32 v51, v15, v15
	v_lshlrev_b32_e32 v54, 16, v77
	global_store_short v2, v51, s[40:41]
	v_fma_f32 v15, v85, v15, v54
	s_add_u32 s40, s40, 0x40000
	s_addc_u32 s41, s41, 0
	v_cvt_pk_bf16_f32 v52, v15, v15
	v_lshlrev_b32_e32 v54, 16, v78
	global_store_short v2, v52, s[40:41]
	v_fma_f32 v15, v86, v15, v54
	s_add_u32 s40, s40, 0x40000
	s_addc_u32 s41, s41, 0
	v_cvt_pk_bf16_f32 v53, v15, v15
	v_lshlrev_b32_e32 v54, 16, v79
	global_store_short v2, v53, s[40:41]
	v_fma_f32 v15, v87, v15, v54
	s_add_u32 s40, s40, 0x40000
	s_addc_u32 s41, s41, 0
	v_cvt_pk_bf16_f32 v50, v15, v15
	v_lshlrev_b32_e32 v54, 16, v80
	global_store_short v2, v50, s[40:41]
	v_fma_f32 v15, v88, v15, v54
	s_add_u32 s40, s40, 0x40000
	s_addc_u32 s41, s41, 0
	v_cvt_pk_bf16_f32 v51, v15, v15
	v_lshlrev_b32_e32 v54, 16, v81
	global_store_short v2, v51, s[40:41]
	v_fma_f32 v15, v89, v15, v54
	s_add_u32 s40, s40, 0x40000
	s_addc_u32 s41, s41, 0
	v_cvt_pk_bf16_f32 v52, v15, v15
	v_lshlrev_b32_e32 v54, 16, v82
	global_store_short v2, v52, s[40:41]
	v_fma_f32 v15, v90, v15, v54
	s_add_u32 s40, s40, 0x40000
	s_addc_u32 s41, s41, 0
	v_cvt_pk_bf16_f32 v53, v15, v15
	v_lshlrev_b32_e32 v54, 16, v83
	global_store_short v2, v53, s[40:41]
	v_fma_f32 v15, v91, v15, v54
	s_add_u32 s40, s40, 0x40000
	s_addc_u32 s41, s41, 0
	global_load_ushort v76, v2, s[98:99]
	global_load_dword v84, v3, s[100:101]
	s_add_u32 s98, s98, 0x40000
	s_addc_u32 s99, s99, 0
	s_add_u32 s100, s100, 0x1000
	s_addc_u32 s101, s101, 0
	global_load_ushort v77, v2, s[98:99]
	global_load_dword v85, v3, s[100:101]
	s_add_u32 s98, s98, 0x40000
	s_addc_u32 s99, s99, 0
	s_add_u32 s100, s100, 0x1000
	s_addc_u32 s101, s101, 0
	global_load_ushort v78, v2, s[98:99]
	global_load_dword v86, v3, s[100:101]
	s_add_u32 s98, s98, 0x40000
	s_addc_u32 s99, s99, 0
	s_add_u32 s100, s100, 0x1000
	s_addc_u32 s101, s101, 0
	global_load_ushort v79, v2, s[98:99]
	global_load_dword v87, v3, s[100:101]
	s_add_u32 s98, s98, 0x40000
	s_addc_u32 s99, s99, 0
	s_add_u32 s100, s100, 0x1000
	s_addc_u32 s101, s101, 0
	global_load_ushort v80, v2, s[98:99]
	global_load_dword v88, v3, s[100:101]
	s_add_u32 s98, s98, 0x40000
	s_addc_u32 s99, s99, 0
	s_add_u32 s100, s100, 0x1000
	s_addc_u32 s101, s101, 0
	global_load_ushort v81, v2, s[98:99]
	global_load_dword v89, v3, s[100:101]
	s_add_u32 s98, s98, 0x40000
	s_addc_u32 s99, s99, 0
	s_add_u32 s100, s100, 0x1000
	s_addc_u32 s101, s101, 0
	global_load_ushort v82, v2, s[98:99]
	global_load_dword v90, v3, s[100:101]
	s_add_u32 s98, s98, 0x40000
	s_addc_u32 s99, s99, 0
	s_add_u32 s100, s100, 0x1000
	s_addc_u32 s101, s101, 0
	global_load_ushort v83, v2, s[98:99]
	global_load_dword v91, v3, s[100:101]
	s_add_u32 s98, s98, 0x40000
	s_addc_u32 s99, s99, 0
	s_add_u32 s100, s100, 0x1000
	s_addc_u32 s101, s101, 0
	s_waitcnt vmcnt(48)
	v_cvt_pk_bf16_f32 v50, v15, v15
	v_lshlrev_b32_e32 v54, 16, v92
	global_store_short v2, v50, s[40:41]
	v_fma_f32 v15, v100, v15, v54
	s_add_u32 s40, s40, 0x40000
	s_addc_u32 s41, s41, 0
	v_cvt_pk_bf16_f32 v51, v15, v15
	v_lshlrev_b32_e32 v54, 16, v93
	global_store_short v2, v51, s[40:41]
	v_fma_f32 v15, v101, v15, v54
	s_add_u32 s40, s40, 0x40000
	s_addc_u32 s41, s41, 0
	v_cvt_pk_bf16_f32 v52, v15, v15
	v_lshlrev_b32_e32 v54, 16, v94
	global_store_short v2, v52, s[40:41]
	v_fma_f32 v15, v102, v15, v54
	s_add_u32 s40, s40, 0x40000
	s_addc_u32 s41, s41, 0
	v_cvt_pk_bf16_f32 v53, v15, v15
	v_lshlrev_b32_e32 v54, 16, v95
	global_store_short v2, v53, s[40:41]
	v_fma_f32 v15, v103, v15, v54
	s_add_u32 s40, s40, 0x40000
	s_addc_u32 s41, s41, 0
	v_cvt_pk_bf16_f32 v50, v15, v15
	v_lshlrev_b32_e32 v54, 16, v96
	global_store_short v2, v50, s[40:41]
	v_fma_f32 v15, v104, v15, v54
	s_add_u32 s40, s40, 0x40000
	s_addc_u32 s41, s41, 0
	v_cvt_pk_bf16_f32 v51, v15, v15
	v_lshlrev_b32_e32 v54, 16, v97
	global_store_short v2, v51, s[40:41]
	v_fma_f32 v15, v105, v15, v54
	s_add_u32 s40, s40, 0x40000
	s_addc_u32 s41, s41, 0
	v_cvt_pk_bf16_f32 v52, v15, v15
	v_lshlrev_b32_e32 v54, 16, v98
	global_store_short v2, v52, s[40:41]
	v_fma_f32 v15, v106, v15, v54
	s_add_u32 s40, s40, 0x40000
	s_addc_u32 s41, s41, 0
	v_cvt_pk_bf16_f32 v53, v15, v15
	v_lshlrev_b32_e32 v54, 16, v99
	global_store_short v2, v53, s[40:41]
	v_fma_f32 v15, v107, v15, v54
	s_add_u32 s40, s40, 0x40000
	s_addc_u32 s41, s41, 0
	global_load_ushort v92, v2, s[98:99]
	global_load_dword v100, v3, s[100:101]
	s_add_u32 s98, s98, 0x40000
	s_addc_u32 s99, s99, 0
	s_add_u32 s100, s100, 0x1000
	s_addc_u32 s101, s101, 0
	global_load_ushort v93, v2, s[98:99]
	global_load_dword v101, v3, s[100:101]
	s_add_u32 s98, s98, 0x40000
	s_addc_u32 s99, s99, 0
	s_add_u32 s100, s100, 0x1000
	s_addc_u32 s101, s101, 0
	global_load_ushort v94, v2, s[98:99]
	global_load_dword v102, v3, s[100:101]
	s_add_u32 s98, s98, 0x40000
	s_addc_u32 s99, s99, 0
	s_add_u32 s100, s100, 0x1000
	s_addc_u32 s101, s101, 0
	global_load_ushort v95, v2, s[98:99]
	global_load_dword v103, v3, s[100:101]
	s_add_u32 s98, s98, 0x40000
	s_addc_u32 s99, s99, 0
	s_add_u32 s100, s100, 0x1000
	s_addc_u32 s101, s101, 0
	global_load_ushort v96, v2, s[98:99]
	global_load_dword v104, v3, s[100:101]
	s_add_u32 s98, s98, 0x40000
	s_addc_u32 s99, s99, 0
	s_add_u32 s100, s100, 0x1000
	s_addc_u32 s101, s101, 0
	global_load_ushort v97, v2, s[98:99]
	global_load_dword v105, v3, s[100:101]
	s_add_u32 s98, s98, 0x40000
	s_addc_u32 s99, s99, 0
	s_add_u32 s100, s100, 0x1000
	s_addc_u32 s101, s101, 0
	global_load_ushort v98, v2, s[98:99]
	global_load_dword v106, v3, s[100:101]
	s_add_u32 s98, s98, 0x40000
	s_addc_u32 s99, s99, 0
	s_add_u32 s100, s100, 0x1000
	s_addc_u32 s101, s101, 0
	global_load_ushort v99, v2, s[98:99]
	global_load_dword v107, v3, s[100:101]
	s_add_u32 s98, s98, 0x40000
	s_addc_u32 s99, s99, 0
	s_add_u32 s100, s100, 0x1000
	s_addc_u32 s101, s101, 0
	s_waitcnt vmcnt(48)
; DI u16 f2bf(float x) { return (u16)(pack2(x, 0.f) & 0xffffu); }
; DI float bf2f(u16 h) { return __uint_as_float(((unsigned)h) << 16); }
; DI void hgrn_scan_phase(const Params& p, char* smem) {
;     ...
;     for (int n0 = 0; n0 < 256; n0 += 8) {
;       float nu[8], nd[8];
;       if (n0 + 8 < 256) {
; #pragma unroll
;         for (int j = 0; j < 8; j++) { nu[j] = bf2f(up[(long)(n0 + 8 + j) * 131072]); nd[j] = dp[(n0 + 8 + j) * 1024]; }
;       } else {
; #pragma unroll
;         for (int j = 0; j < 8; j++) { nu[j] = 0.f; nd[j] = 0.f; }
;       }
; #pragma unroll
;       for (int j = 0; j < 8; j++) { up[(long)(n0 + j) * 131072] = f2bf(S); S = cd[j] * S + cu[j]; }
; #pragma unroll
;       for (int j = 0; j < 8; j++) { cu[j] = nu[j]; cd[j] = nd[j]; }
;     }
	v_cvt_pk_bf16_f32 v50, v15, v15
	v_lshlrev_b32_e32 v54, 16, v60
	global_store_short v2, v50, s[40:41]
	v_fma_f32 v15, v68, v15, v54
	s_add_u32 s40, s40, 0x40000
	s_addc_u32 s41, s41, 0
	v_cvt_pk_bf16_f32 v51, v15, v15
	v_lshlrev_b32_e32 v54, 16, v61
	global_store_short v2, v51, s[40:41]
	v_fma_f32 v15, v69, v15, v54
	s_add_u32 s40, s40, 0x40000
	s_addc_u32 s41, s41, 0
	v_cvt_pk_bf16_f32 v52, v15, v15
	v_lshlrev_b32_e32 v54, 16, v62
	global_store_short v2, v52, s[40:41]
	v_fma_f32 v15, v70, v15, v54
	s_add_u32 s40, s40, 0x40000
	s_addc_u32 s41, s41, 0
	v_cvt_pk_bf16_f32 v53, v15, v15
	v_lshlrev_b32_e32 v54, 16, v63
	global_store_short v2, v53, s[40:41]
	v_fma_f32 v15, v71, v15, v54
	s_add_u32 s40, s40, 0x40000
	s_addc_u32 s41, s41, 0
	v_cvt_pk_bf16_f32 v50, v15, v15
	v_lshlrev_b32_e32 v54, 16, v64
	global_store_short v2, v50, s[40:41]
	v_fma_f32 v15, v72, v15, v54
	s_add_u32 s40, s40, 0x40000
	s_addc_u32 s41, s41, 0
	v_cvt_pk_bf16_f32 v51, v15, v15
	v_lshlrev_b32_e32 v54, 16, v65
	global_store_short v2, v51, s[40:41]
	v_fma_f32 v15, v73, v15, v54
	s_add_u32 s40, s40, 0x40000
	s_addc_u32 s41, s41, 0
	v_cvt_pk_bf16_f32 v52, v15, v15
	v_lshlrev_b32_e32 v54, 16, v66
	global_store_short v2, v52, s[40:41]
	v_fma_f32 v15, v74, v15, v54
	s_add_u32 s40, s40, 0x40000
	s_addc_u32 s41, s41, 0
	v_cvt_pk_bf16_f32 v53, v15, v15
	v_lshlrev_b32_e32 v54, 16, v67
	global_store_short v2, v53, s[40:41]
	v_fma_f32 v15, v75, v15, v54
	s_add_u32 s40, s40, 0x40000
	s_addc_u32 s41, s41, 0
	global_load_ushort v60, v2, s[98:99]
	global_load_dword v68, v3, s[100:101]
	s_add_u32 s98, s98, 0x40000
	s_addc_u32 s99, s99, 0
	s_add_u32 s100, s100, 0x1000
	s_addc_u32 s101, s101, 0
	global_load_ushort v61, v2, s[98:99]
	global_load_dword v69, v3, s[100:101]
	s_add_u32 s98, s98, 0x40000
	s_addc_u32 s99, s99, 0
	s_add_u32 s100, s100, 0x1000
	s_addc_u32 s101, s101, 0
	global_load_ushort v62, v2, s[98:99]
	global_load_dword v70, v3, s[100:101]
	s_add_u32 s98, s98, 0x40000
	s_addc_u32 s99, s99, 0
	s_add_u32 s100, s100, 0x1000
	s_addc_u32 s101, s101, 0
	global_load_ushort v63, v2, s[98:99]
	global_load_dword v71, v3, s[100:101]
	s_add_u32 s98, s98, 0x40000
	s_addc_u32 s99, s99, 0
	s_add_u32 s100, s100, 0x1000
	s_addc_u32 s101, s101, 0
	global_load_ushort v64, v2, s[98:99]
	global_load_dword v72, v3, s[100:101]
	s_add_u32 s98, s98, 0x40000
	s_addc_u32 s99, s99, 0
	s_add_u32 s100, s100, 0x1000
	s_addc_u32 s101, s101, 0
	global_load_ushort v65, v2, s[98:99]
	global_load_dword v73, v3, s[100:101]
	s_add_u32 s98, s98, 0x40000
	s_addc_u32 s99, s99, 0
	s_add_u32 s100, s100, 0x1000
	s_addc_u32 s101, s101, 0
	global_load_ushort v66, v2, s[98:99]
	global_load_dword v74, v3, s[100:101]
	s_add_u32 s98, s98, 0x40000
	s_addc_u32 s99, s99, 0
	s_add_u32 s100, s100, 0x1000
	s_addc_u32 s101, s101, 0
	global_load_ushort v67, v2, s[98:99]
	global_load_dword v75, v3, s[100:101]
	s_add_u32 s98, s98, 0x40000
	s_addc_u32 s99, s99, 0
	s_add_u32 s100, s100, 0x1000
	s_addc_u32 s101, s101, 0
	s_waitcnt vmcnt(48)
	v_cvt_pk_bf16_f32 v50, v15, v15
	v_lshlrev_b32_e32 v54, 16, v76
	global_store_short v2, v50, s[40:41]
	v_fma_f32 v15, v84, v15, v54
	s_add_u32 s40, s40, 0x40000
	s_addc_u32 s41, s41, 0
	v_cvt_pk_bf16_f32 v51, v15, v15
	v_lshlrev_b32_e32 v54, 16, v77
	global_store_short v2, v51, s[40:41]
	v_fma_f32 v15, v85, v15, v54
	s_add_u32 s40, s40, 0x40000
	s_addc_u32 s41, s41, 0
	v_cvt_pk_bf16_f32 v52, v15, v15
	v_lshlrev_b32_e32 v54, 16, v78
	global_store_short v2, v52, s[40:41]
	v_fma_f32 v15, v86, v15, v54
	s_add_u32 s40, s40, 0x40000
	s_addc_u32 s41, s41, 0
	v_cvt_pk_bf16_f32 v53, v15, v15
	v_lshlrev_b32_e32 v54, 16, v79
	global_store_short v2, v53, s[40:41]
	v_fma_f32 v15, v87, v15, v54
	s_add_u32 s40, s40, 0x40000
	s_addc_u32 s41, s41, 0
	v_cvt_pk_bf16_f32 v50, v15, v15
	v_lshlrev_b32_e32 v54, 16, v80
	global_store_short v2, v50, s[40:41]
	v_fma_f32 v15, v88, v15, v54
	s_add_u32 s40, s40, 0x40000
	s_addc_u32 s41, s41, 0
	v_cvt_pk_bf16_f32 v51, v15, v15
	v_lshlrev_b32_e32 v54, 16, v81
	global_store_short v2, v51, s[40:41]
	v_fma_f32 v15, v89, v15, v54
	s_add_u32 s40, s40, 0x40000
	s_addc_u32 s41, s41, 0
	v_cvt_pk_bf16_f32 v52, v15, v15
	v_lshlrev_b32_e32 v54, 16, v82
	global_store_short v2, v52, s[40:41]
	v_fma_f32 v15, v90, v15, v54
	s_add_u32 s40, s40, 0x40000
	s_addc_u32 s41, s41, 0
	v_cvt_pk_bf16_f32 v53, v15, v15
	v_lshlrev_b32_e32 v54, 16, v83
	global_store_short v2, v53, s[40:41]
	v_fma_f32 v15, v91, v15, v54
	s_add_u32 s40, s40, 0x40000
	s_addc_u32 s41, s41, 0
	global_load_ushort v76, v2, s[98:99]
	global_load_dword v84, v3, s[100:101]
	s_add_u32 s98, s98, 0x40000
	s_addc_u32 s99, s99, 0
	s_add_u32 s100, s100, 0x1000
	s_addc_u32 s101, s101, 0
	global_load_ushort v77, v2, s[98:99]
	global_load_dword v85, v3, s[100:101]
	s_add_u32 s98, s98, 0x40000
	s_addc_u32 s99, s99, 0
	s_add_u32 s100, s100, 0x1000
	s_addc_u32 s101, s101, 0
	global_load_ushort v78, v2, s[98:99]
	global_load_dword v86, v3, s[100:101]
	s_add_u32 s98, s98, 0x40000
	s_addc_u32 s99, s99, 0
	s_add_u32 s100, s100, 0x1000
	s_addc_u32 s101, s101, 0
	global_load_ushort v79, v2, s[98:99]
	global_load_dword v87, v3, s[100:101]
	s_add_u32 s98, s98, 0x40000
	s_addc_u32 s99, s99, 0
	s_add_u32 s100, s100, 0x1000
	s_addc_u32 s101, s101, 0
	global_load_ushort v80, v2, s[98:99]
	global_load_dword v88, v3, s[100:101]
	s_add_u32 s98, s98, 0x40000
	s_addc_u32 s99, s99, 0
	s_add_u32 s100, s100, 0x1000
	s_addc_u32 s101, s101, 0
	global_load_ushort v81, v2, s[98:99]
	global_load_dword v89, v3, s[100:101]
	s_add_u32 s98, s98, 0x40000
	s_addc_u32 s99, s99, 0
	s_add_u32 s100, s100, 0x1000
	s_addc_u32 s101, s101, 0
	global_load_ushort v82, v2, s[98:99]
	global_load_dword v90, v3, s[100:101]
	s_add_u32 s98, s98, 0x40000
	s_addc_u32 s99, s99, 0
	s_add_u32 s100, s100, 0x1000
	s_addc_u32 s101, s101, 0
	global_load_ushort v83, v2, s[98:99]
	global_load_dword v91, v3, s[100:101]
	s_add_u32 s98, s98, 0x40000
	s_addc_u32 s99, s99, 0
	s_add_u32 s100, s100, 0x1000
	s_addc_u32 s101, s101, 0
	s_waitcnt vmcnt(48)
; DI u16 f2bf(float x) { return (u16)(pack2(x, 0.f) & 0xffffu); }
; DI float bf2f(u16 h) { return __uint_as_float(((unsigned)h) << 16); }
; DI void hgrn_scan_phase(const Params& p, char* smem) {
;     ...
;     for (int n0 = 0; n0 < 256; n0 += 8) {
;       float nu[8], nd[8];
;       if (n0 + 8 < 256) {
; #pragma unroll
;         for (int j = 0; j < 8; j++) { nu[j] = bf2f(up[(long)(n0 + 8 + j) * 131072]); nd[j] = dp[(n0 + 8 + j) * 1024]; }
;       } else {
; #pragma unroll
;         for (int j = 0; j < 8; j++) { nu[j] = 0.f; nd[j] = 0.f; }
;       }
; #pragma unroll
;       for (int j = 0; j < 8; j++) { up[(long)(n0 + j) * 131072] = f2bf(S); S = cd[j] * S + cu[j]; }
; #pragma unroll
;       for (int j = 0; j < 8; j++) { cu[j] = nu[j]; cd[j] = nd[j]; }
;     }
	v_cvt_pk_bf16_f32 v50, v15, v15
	v_lshlrev_b32_e32 v54, 16, v92
	global_store_short v2, v50, s[40:41]
	v_fma_f32 v15, v100, v15, v54
	s_add_u32 s40, s40, 0x40000
	s_addc_u32 s41, s41, 0
	v_cvt_pk_bf16_f32 v51, v15, v15
	v_lshlrev_b32_e32 v54, 16, v93
	global_store_short v2, v51, s[40:41]
	v_fma_f32 v15, v101, v15, v54
	s_add_u32 s40, s40, 0x40000
	s_addc_u32 s41, s41, 0
	v_cvt_pk_bf16_f32 v52, v15, v15
	v_lshlrev_b32_e32 v54, 16, v94
	global_store_short v2, v52, s[40:41]
	v_fma_f32 v15, v102, v15, v54
	s_add_u32 s40, s40, 0x40000
	s_addc_u32 s41, s41, 0
	v_cvt_pk_bf16_f32 v53, v15, v15
	v_lshlrev_b32_e32 v54, 16, v95
	global_store_short v2, v53, s[40:41]
	v_fma_f32 v15, v103, v15, v54
	s_add_u32 s40, s40, 0x40000
	s_addc_u32 s41, s41, 0
	v_cvt_pk_bf16_f32 v50, v15, v15
	v_lshlrev_b32_e32 v54, 16, v96
	global_store_short v2, v50, s[40:41]
	v_fma_f32 v15, v104, v15, v54
	s_add_u32 s40, s40, 0x40000
	s_addc_u32 s41, s41, 0
	v_cvt_pk_bf16_f32 v51, v15, v15
	v_lshlrev_b32_e32 v54, 16, v97
	global_store_short v2, v51, s[40:41]
	v_fma_f32 v15, v105, v15, v54
	s_add_u32 s40, s40, 0x40000
	s_addc_u32 s41, s41, 0
	v_cvt_pk_bf16_f32 v52, v15, v15
	v_lshlrev_b32_e32 v54, 16, v98
	global_store_short v2, v52, s[40:41]
	v_fma_f32 v15, v106, v15, v54
	s_add_u32 s40, s40, 0x40000
	s_addc_u32 s41, s41, 0
	v_cvt_pk_bf16_f32 v53, v15, v15
	v_lshlrev_b32_e32 v54, 16, v99
	global_store_short v2, v53, s[40:41]
	v_fma_f32 v15, v107, v15, v54
	s_add_u32 s40, s40, 0x40000
	s_addc_u32 s41, s41, 0
	global_load_ushort v92, v2, s[98:99]
	global_load_dword v100, v3, s[100:101]
	s_add_u32 s98, s98, 0x40000
	s_addc_u32 s99, s99, 0
	s_add_u32 s100, s100, 0x1000
	s_addc_u32 s101, s101, 0
	global_load_ushort v93, v2, s[98:99]
	global_load_dword v101, v3, s[100:101]
	s_add_u32 s98, s98, 0x40000
	s_addc_u32 s99, s99, 0
	s_add_u32 s100, s100, 0x1000
	s_addc_u32 s101, s101, 0
	global_load_ushort v94, v2, s[98:99]
	global_load_dword v102, v3, s[100:101]
	s_add_u32 s98, s98, 0x40000
	s_addc_u32 s99, s99, 0
	s_add_u32 s100, s100, 0x1000
	s_addc_u32 s101, s101, 0
	global_load_ushort v95, v2, s[98:99]
	global_load_dword v103, v3, s[100:101]
	s_add_u32 s98, s98, 0x40000
	s_addc_u32 s99, s99, 0
	s_add_u32 s100, s100, 0x1000
	s_addc_u32 s101, s101, 0
	global_load_ushort v96, v2, s[98:99]
	global_load_dword v104, v3, s[100:101]
	s_add_u32 s98, s98, 0x40000
	s_addc_u32 s99, s99, 0
	s_add_u32 s100, s100, 0x1000
	s_addc_u32 s101, s101, 0
	global_load_ushort v97, v2, s[98:99]
	global_load_dword v105, v3, s[100:101]
	s_add_u32 s98, s98, 0x40000
	s_addc_u32 s99, s99, 0
	s_add_u32 s100, s100, 0x1000
	s_addc_u32 s101, s101, 0
	global_load_ushort v98, v2, s[98:99]
	global_load_dword v106, v3, s[100:101]
	s_add_u32 s98, s98, 0x40000
	s_addc_u32 s99, s99, 0
	s_add_u32 s100, s100, 0x1000
	s_addc_u32 s101, s101, 0
	global_load_ushort v99, v2, s[98:99]
	global_load_dword v107, v3, s[100:101]
	s_add_u32 s98, s98, 0x40000
	s_addc_u32 s99, s99, 0
	s_add_u32 s100, s100, 0x1000
	s_addc_u32 s101, s101, 0
	s_waitcnt vmcnt(48)
	v_cvt_pk_bf16_f32 v50, v15, v15
	v_lshlrev_b32_e32 v54, 16, v60
	global_store_short v2, v50, s[40:41]
	v_fma_f32 v15, v68, v15, v54
	s_add_u32 s40, s40, 0x40000
	s_addc_u32 s41, s41, 0
	v_cvt_pk_bf16_f32 v51, v15, v15
	v_lshlrev_b32_e32 v54, 16, v61
	global_store_short v2, v51, s[40:41]
	v_fma_f32 v15, v69, v15, v54
	s_add_u32 s40, s40, 0x40000
	s_addc_u32 s41, s41, 0
	v_cvt_pk_bf16_f32 v52, v15, v15
	v_lshlrev_b32_e32 v54, 16, v62
	global_store_short v2, v52, s[40:41]
	v_fma_f32 v15, v70, v15, v54
	s_add_u32 s40, s40, 0x40000
	s_addc_u32 s41, s41, 0
	v_cvt_pk_bf16_f32 v53, v15, v15
	v_lshlrev_b32_e32 v54, 16, v63
	global_store_short v2, v53, s[40:41]
	v_fma_f32 v15, v71, v15, v54
	s_add_u32 s40, s40, 0x40000
	s_addc_u32 s41, s41, 0
	v_cvt_pk_bf16_f32 v50, v15, v15
	v_lshlrev_b32_e32 v54, 16, v64
	global_store_short v2, v50, s[40:41]
	v_fma_f32 v15, v72, v15, v54
	s_add_u32 s40, s40, 0x40000
	s_addc_u32 s41, s41, 0
	v_cvt_pk_bf16_f32 v51, v15, v15
	v_lshlrev_b32_e32 v54, 16, v65
	global_store_short v2, v51, s[40:41]
	v_fma_f32 v15, v73, v15, v54
	s_add_u32 s40, s40, 0x40000
	s_addc_u32 s41, s41, 0
	v_cvt_pk_bf16_f32 v52, v15, v15
	v_lshlrev_b32_e32 v54, 16, v66
	global_store_short v2, v52, s[40:41]
	v_fma_f32 v15, v74, v15, v54
	s_add_u32 s40, s40, 0x40000
	s_addc_u32 s41, s41, 0
	v_cvt_pk_bf16_f32 v53, v15, v15
	v_lshlrev_b32_e32 v54, 16, v67
	global_store_short v2, v53, s[40:41]
	v_fma_f32 v15, v75, v15, v54
	s_add_u32 s40, s40, 0x40000
	s_addc_u32 s41, s41, 0
	global_load_ushort v60, v2, s[98:99]
	global_load_dword v68, v3, s[100:101]
	s_add_u32 s98, s98, 0x40000
	s_addc_u32 s99, s99, 0
	s_add_u32 s100, s100, 0x1000
	s_addc_u32 s101, s101, 0
	global_load_ushort v61, v2, s[98:99]
	global_load_dword v69, v3, s[100:101]
	s_add_u32 s98, s98, 0x40000
	s_addc_u32 s99, s99, 0
	s_add_u32 s100, s100, 0x1000
	s_addc_u32 s101, s101, 0
	global_load_ushort v62, v2, s[98:99]
	global_load_dword v70, v3, s[100:101]
	s_add_u32 s98, s98, 0x40000
	s_addc_u32 s99, s99, 0
	s_add_u32 s100, s100, 0x1000
	s_addc_u32 s101, s101, 0
	global_load_ushort v63, v2, s[98:99]
	global_load_dword v71, v3, s[100:101]
	s_add_u32 s98, s98, 0x40000
	s_addc_u32 s99, s99, 0
	s_add_u32 s100, s100, 0x1000
	s_addc_u32 s101, s101, 0
	global_load_ushort v64, v2, s[98:99]
	global_load_dword v72, v3, s[100:101]
	s_add_u32 s98, s98, 0x40000
	s_addc_u32 s99, s99, 0
	s_add_u32 s100, s100, 0x1000
	s_addc_u32 s101, s101, 0
	global_load_ushort v65, v2, s[98:99]
	global_load_dword v73, v3, s[100:101]
	s_add_u32 s98, s98, 0x40000
	s_addc_u32 s99, s99, 0
	s_add_u32 s100, s100, 0x1000
	s_addc_u32 s101, s101, 0
	global_load_ushort v66, v2, s[98:99]
	global_load_dword v74, v3, s[100:101]
	s_add_u32 s98, s98, 0x40000
	s_addc_u32 s99, s99, 0
	s_add_u32 s100, s100, 0x1000
	s_addc_u32 s101, s101, 0
	global_load_ushort v67, v2, s[98:99]
	global_load_dword v75, v3, s[100:101]
	s_add_u32 s98, s98, 0x40000
	s_addc_u32 s99, s99, 0
	s_add_u32 s100, s100, 0x1000
	s_addc_u32 s101, s101, 0
	s_waitcnt vmcnt(48)
; DI u16 f2bf(float x) { return (u16)(pack2(x, 0.f) & 0xffffu); }
; DI float bf2f(u16 h) { return __uint_as_float(((unsigned)h) << 16); }
; DI void hgrn_scan_phase(const Params& p, char* smem) {
;     ...
;     for (int n0 = 0; n0 < 256; n0 += 8) {
;       float nu[8], nd[8];
;       if (n0 + 8 < 256) {
; #pragma unroll
;         for (int j = 0; j < 8; j++) { nu[j] = bf2f(up[(long)(n0 + 8 + j) * 131072]); nd[j] = dp[(n0 + 8 + j) * 1024]; }
;       } else {
; #pragma unroll
;         for (int j = 0; j < 8; j++) { nu[j] = 0.f; nd[j] = 0.f; }
;       }
; #pragma unroll
;       for (int j = 0; j < 8; j++) { up[(long)(n0 + j) * 131072] = f2bf(S); S = cd[j] * S + cu[j]; }
; #pragma unroll
;       for (int j = 0; j < 8; j++) { cu[j] = nu[j]; cd[j] = nd[j]; }
;     }
	v_cvt_pk_bf16_f32 v50, v15, v15
	v_lshlrev_b32_e32 v54, 16, v76
	global_store_short v2, v50, s[40:41]
	v_fma_f32 v15, v84, v15, v54
	s_add_u32 s40, s40, 0x40000
	s_addc_u32 s41, s41, 0
	v_cvt_pk_bf16_f32 v51, v15, v15
	v_lshlrev_b32_e32 v54, 16, v77
	global_store_short v2, v51, s[40:41]
	v_fma_f32 v15, v85, v15, v54
	s_add_u32 s40, s40, 0x40000
	s_addc_u32 s41, s41, 0
	v_cvt_pk_bf16_f32 v52, v15, v15
	v_lshlrev_b32_e32 v54, 16, v78
	global_store_short v2, v52, s[40:41]
	v_fma_f32 v15, v86, v15, v54
	s_add_u32 s40, s40, 0x40000
	s_addc_u32 s41, s41, 0
	v_cvt_pk_bf16_f32 v53, v15, v15
	v_lshlrev_b32_e32 v54, 16, v79
	global_store_short v2, v53, s[40:41]
	v_fma_f32 v15, v87, v15, v54
	s_add_u32 s40, s40, 0x40000
	s_addc_u32 s41, s41, 0
	v_cvt_pk_bf16_f32 v50, v15, v15
	v_lshlrev_b32_e32 v54, 16, v80
	global_store_short v2, v50, s[40:41]
	v_fma_f32 v15, v88, v15, v54
	s_add_u32 s40, s40, 0x40000
	s_addc_u32 s41, s41, 0
	v_cvt_pk_bf16_f32 v51, v15, v15
	v_lshlrev_b32_e32 v54, 16, v81
	global_store_short v2, v51, s[40:41]
	v_fma_f32 v15, v89, v15, v54
	s_add_u32 s40, s40, 0x40000
	s_addc_u32 s41, s41, 0
	v_cvt_pk_bf16_f32 v52, v15, v15
	v_lshlrev_b32_e32 v54, 16, v82
	global_store_short v2, v52, s[40:41]
	v_fma_f32 v15, v90, v15, v54
	s_add_u32 s40, s40, 0x40000
	s_addc_u32 s41, s41, 0
	v_cvt_pk_bf16_f32 v53, v15, v15
	v_lshlrev_b32_e32 v54, 16, v83
	global_store_short v2, v53, s[40:41]
	v_fma_f32 v15, v91, v15, v54
	s_add_u32 s40, s40, 0x40000
	s_addc_u32 s41, s41, 0
	global_load_ushort v76, v2, s[98:99]
	global_load_dword v84, v3, s[100:101]
	s_add_u32 s98, s98, 0x40000
	s_addc_u32 s99, s99, 0
	s_add_u32 s100, s100, 0x1000
	s_addc_u32 s101, s101, 0
	global_load_ushort v77, v2, s[98:99]
	global_load_dword v85, v3, s[100:101]
	s_add_u32 s98, s98, 0x40000
	s_addc_u32 s99, s99, 0
	s_add_u32 s100, s100, 0x1000
	s_addc_u32 s101, s101, 0
	global_load_ushort v78, v2, s[98:99]
	global_load_dword v86, v3, s[100:101]
	s_add_u32 s98, s98, 0x40000
	s_addc_u32 s99, s99, 0
	s_add_u32 s100, s100, 0x1000
	s_addc_u32 s101, s101, 0
	global_load_ushort v79, v2, s[98:99]
	global_load_dword v87, v3, s[100:101]
	s_add_u32 s98, s98, 0x40000
	s_addc_u32 s99, s99, 0
	s_add_u32 s100, s100, 0x1000
	s_addc_u32 s101, s101, 0
	global_load_ushort v80, v2, s[98:99]
	global_load_dword v88, v3, s[100:101]
	s_add_u32 s98, s98, 0x40000
	s_addc_u32 s99, s99, 0
	s_add_u32 s100, s100, 0x1000
	s_addc_u32 s101, s101, 0
	global_load_ushort v81, v2, s[98:99]
	global_load_dword v89, v3, s[100:101]
	s_add_u32 s98, s98, 0x40000
	s_addc_u32 s99, s99, 0
	s_add_u32 s100, s100, 0x1000
	s_addc_u32 s101, s101, 0
	global_load_ushort v82, v2, s[98:99]
	global_load_dword v90, v3, s[100:101]
	s_add_u32 s98, s98, 0x40000
	s_addc_u32 s99, s99, 0
	s_add_u32 s100, s100, 0x1000
	s_addc_u32 s101, s101, 0
	global_load_ushort v83, v2, s[98:99]
	global_load_dword v91, v3, s[100:101]
	s_add_u32 s98, s98, 0x40000
	s_addc_u32 s99, s99, 0
	s_add_u32 s100, s100, 0x1000
	s_addc_u32 s101, s101, 0
	s_waitcnt vmcnt(48)
	v_cvt_pk_bf16_f32 v50, v15, v15
	v_lshlrev_b32_e32 v54, 16, v92
	global_store_short v2, v50, s[40:41]
	v_fma_f32 v15, v100, v15, v54
	s_add_u32 s40, s40, 0x40000
	s_addc_u32 s41, s41, 0
	v_cvt_pk_bf16_f32 v51, v15, v15
	v_lshlrev_b32_e32 v54, 16, v93
	global_store_short v2, v51, s[40:41]
	v_fma_f32 v15, v101, v15, v54
	s_add_u32 s40, s40, 0x40000
	s_addc_u32 s41, s41, 0
	v_cvt_pk_bf16_f32 v52, v15, v15
	v_lshlrev_b32_e32 v54, 16, v94
	global_store_short v2, v52, s[40:41]
	v_fma_f32 v15, v102, v15, v54
	s_add_u32 s40, s40, 0x40000
	s_addc_u32 s41, s41, 0
	v_cvt_pk_bf16_f32 v53, v15, v15
	v_lshlrev_b32_e32 v54, 16, v95
	global_store_short v2, v53, s[40:41]
	v_fma_f32 v15, v103, v15, v54
	s_add_u32 s40, s40, 0x40000
	s_addc_u32 s41, s41, 0
	v_cvt_pk_bf16_f32 v50, v15, v15
	v_lshlrev_b32_e32 v54, 16, v96
	global_store_short v2, v50, s[40:41]
	v_fma_f32 v15, v104, v15, v54
	s_add_u32 s40, s40, 0x40000
	s_addc_u32 s41, s41, 0
	v_cvt_pk_bf16_f32 v51, v15, v15
	v_lshlrev_b32_e32 v54, 16, v97
	global_store_short v2, v51, s[40:41]
	v_fma_f32 v15, v105, v15, v54
	s_add_u32 s40, s40, 0x40000
	s_addc_u32 s41, s41, 0
	v_cvt_pk_bf16_f32 v52, v15, v15
	v_lshlrev_b32_e32 v54, 16, v98
	global_store_short v2, v52, s[40:41]
	v_fma_f32 v15, v106, v15, v54
	s_add_u32 s40, s40, 0x40000
	s_addc_u32 s41, s41, 0
	v_cvt_pk_bf16_f32 v53, v15, v15
	v_lshlrev_b32_e32 v54, 16, v99
	global_store_short v2, v53, s[40:41]
	v_fma_f32 v15, v107, v15, v54
	s_add_u32 s40, s40, 0x40000
	s_addc_u32 s41, s41, 0
	global_load_ushort v92, v2, s[98:99]
	global_load_dword v100, v3, s[100:101]
	s_add_u32 s98, s98, 0x40000
	s_addc_u32 s99, s99, 0
	s_add_u32 s100, s100, 0x1000
	s_addc_u32 s101, s101, 0
	global_load_ushort v93, v2, s[98:99]
	global_load_dword v101, v3, s[100:101]
	s_add_u32 s98, s98, 0x40000
	s_addc_u32 s99, s99, 0
	s_add_u32 s100, s100, 0x1000
	s_addc_u32 s101, s101, 0
	global_load_ushort v94, v2, s[98:99]
	global_load_dword v102, v3, s[100:101]
	s_add_u32 s98, s98, 0x40000
	s_addc_u32 s99, s99, 0
	s_add_u32 s100, s100, 0x1000
	s_addc_u32 s101, s101, 0
	global_load_ushort v95, v2, s[98:99]
	global_load_dword v103, v3, s[100:101]
	s_add_u32 s98, s98, 0x40000
	s_addc_u32 s99, s99, 0
	s_add_u32 s100, s100, 0x1000
	s_addc_u32 s101, s101, 0
	global_load_ushort v96, v2, s[98:99]
	global_load_dword v104, v3, s[100:101]
	s_add_u32 s98, s98, 0x40000
	s_addc_u32 s99, s99, 0
	s_add_u32 s100, s100, 0x1000
	s_addc_u32 s101, s101, 0
	global_load_ushort v97, v2, s[98:99]
	global_load_dword v105, v3, s[100:101]
	s_add_u32 s98, s98, 0x40000
	s_addc_u32 s99, s99, 0
	s_add_u32 s100, s100, 0x1000
	s_addc_u32 s101, s101, 0
	global_load_ushort v98, v2, s[98:99]
	global_load_dword v106, v3, s[100:101]
	s_add_u32 s98, s98, 0x40000
	s_addc_u32 s99, s99, 0
	s_add_u32 s100, s100, 0x1000
	s_addc_u32 s101, s101, 0
	global_load_ushort v99, v2, s[98:99]
	global_load_dword v107, v3, s[100:101]
	s_add_u32 s98, s98, 0x40000
	s_addc_u32 s99, s99, 0
	s_add_u32 s100, s100, 0x1000
	s_addc_u32 s101, s101, 0
	s_waitcnt vmcnt(48)
; DI u16 f2bf(float x) { return (u16)(pack2(x, 0.f) & 0xffffu); }
; DI float bf2f(u16 h) { return __uint_as_float(((unsigned)h) << 16); }
; DI void hgrn_scan_phase(const Params& p, char* smem) {
;     ...
;     for (int n0 = 0; n0 < 256; n0 += 8) {
;       float nu[8], nd[8];
;       if (n0 + 8 < 256) {
; #pragma unroll
;         for (int j = 0; j < 8; j++) { nu[j] = bf2f(up[(long)(n0 + 8 + j) * 131072]); nd[j] = dp[(n0 + 8 + j) * 1024]; }
;       } else {
; #pragma unroll
;         for (int j = 0; j < 8; j++) { nu[j] = 0.f; nd[j] = 0.f; }
;       }
; #pragma unroll
;       for (int j = 0; j < 8; j++) { up[(long)(n0 + j) * 131072] = f2bf(S); S = cd[j] * S + cu[j]; }
; #pragma unroll
;       for (int j = 0; j < 8; j++) { cu[j] = nu[j]; cd[j] = nd[j]; }
;     }
	v_cvt_pk_bf16_f32 v50, v15, v15
	v_lshlrev_b32_e32 v54, 16, v60
	global_store_short v2, v50, s[40:41]
	v_fma_f32 v15, v68, v15, v54
	s_add_u32 s40, s40, 0x40000
	s_addc_u32 s41, s41, 0
	v_cvt_pk_bf16_f32 v51, v15, v15
	v_lshlrev_b32_e32 v54, 16, v61
	global_store_short v2, v51, s[40:41]
	v_fma_f32 v15, v69, v15, v54
	s_add_u32 s40, s40, 0x40000
	s_addc_u32 s41, s41, 0
	v_cvt_pk_bf16_f32 v52, v15, v15
	v_lshlrev_b32_e32 v54, 16, v62
	global_store_short v2, v52, s[40:41]
	v_fma_f32 v15, v70, v15, v54
	s_add_u32 s40, s40, 0x40000
	s_addc_u32 s41, s41, 0
	v_cvt_pk_bf16_f32 v53, v15, v15
	v_lshlrev_b32_e32 v54, 16, v63
	global_store_short v2, v53, s[40:41]
	v_fma_f32 v15, v71, v15, v54
	s_add_u32 s40, s40, 0x40000
	s_addc_u32 s41, s41, 0
	v_cvt_pk_bf16_f32 v50, v15, v15
	v_lshlrev_b32_e32 v54, 16, v64
	global_store_short v2, v50, s[40:41]
	v_fma_f32 v15, v72, v15, v54
	s_add_u32 s40, s40, 0x40000
	s_addc_u32 s41, s41, 0
	v_cvt_pk_bf16_f32 v51, v15, v15
	v_lshlrev_b32_e32 v54, 16, v65
	global_store_short v2, v51, s[40:41]
	v_fma_f32 v15, v73, v15, v54
	s_add_u32 s40, s40, 0x40000
	s_addc_u32 s41, s41, 0
	v_cvt_pk_bf16_f32 v52, v15, v15
	v_lshlrev_b32_e32 v54, 16, v66
	global_store_short v2, v52, s[40:41]
	v_fma_f32 v15, v74, v15, v54
	s_add_u32 s40, s40, 0x40000
	s_addc_u32 s41, s41, 0
	v_cvt_pk_bf16_f32 v53, v15, v15
	v_lshlrev_b32_e32 v54, 16, v67
	global_store_short v2, v53, s[40:41]
	v_fma_f32 v15, v75, v15, v54
	s_add_u32 s40, s40, 0x40000
	s_addc_u32 s41, s41, 0
	global_load_ushort v60, v2, s[98:99]
	global_load_dword v68, v3, s[100:101]
	s_add_u32 s98, s98, 0x40000
	s_addc_u32 s99, s99, 0
	s_add_u32 s100, s100, 0x1000
	s_addc_u32 s101, s101, 0
	global_load_ushort v61, v2, s[98:99]
	global_load_dword v69, v3, s[100:101]
	s_add_u32 s98, s98, 0x40000
	s_addc_u32 s99, s99, 0
	s_add_u32 s100, s100, 0x1000
	s_addc_u32 s101, s101, 0
	global_load_ushort v62, v2, s[98:99]
	global_load_dword v70, v3, s[100:101]
	s_add_u32 s98, s98, 0x40000
	s_addc_u32 s99, s99, 0
	s_add_u32 s100, s100, 0x1000
	s_addc_u32 s101, s101, 0
	global_load_ushort v63, v2, s[98:99]
	global_load_dword v71, v3, s[100:101]
	s_add_u32 s98, s98, 0x40000
	s_addc_u32 s99, s99, 0
	s_add_u32 s100, s100, 0x1000
	s_addc_u32 s101, s101, 0
	global_load_ushort v64, v2, s[98:99]
	global_load_dword v72, v3, s[100:101]
	s_add_u32 s98, s98, 0x40000
	s_addc_u32 s99, s99, 0
	s_add_u32 s100, s100, 0x1000
	s_addc_u32 s101, s101, 0
	global_load_ushort v65, v2, s[98:99]
	global_load_dword v73, v3, s[100:101]
	s_add_u32 s98, s98, 0x40000
	s_addc_u32 s99, s99, 0
	s_add_u32 s100, s100, 0x1000
	s_addc_u32 s101, s101, 0
	global_load_ushort v66, v2, s[98:99]
	global_load_dword v74, v3, s[100:101]
	s_add_u32 s98, s98, 0x40000
	s_addc_u32 s99, s99, 0
	s_add_u32 s100, s100, 0x1000
	s_addc_u32 s101, s101, 0
	global_load_ushort v67, v2, s[98:99]
	global_load_dword v75, v3, s[100:101]
	s_add_u32 s98, s98, 0x40000
	s_addc_u32 s99, s99, 0
	s_add_u32 s100, s100, 0x1000
	s_addc_u32 s101, s101, 0
	s_waitcnt vmcnt(48)
	v_cvt_pk_bf16_f32 v50, v15, v15
	v_lshlrev_b32_e32 v54, 16, v76
	global_store_short v2, v50, s[40:41]
	v_fma_f32 v15, v84, v15, v54
	s_add_u32 s40, s40, 0x40000
	s_addc_u32 s41, s41, 0
	v_cvt_pk_bf16_f32 v51, v15, v15
	v_lshlrev_b32_e32 v54, 16, v77
	global_store_short v2, v51, s[40:41]
	v_fma_f32 v15, v85, v15, v54
	s_add_u32 s40, s40, 0x40000
	s_addc_u32 s41, s41, 0
	v_cvt_pk_bf16_f32 v52, v15, v15
	v_lshlrev_b32_e32 v54, 16, v78
	global_store_short v2, v52, s[40:41]
	v_fma_f32 v15, v86, v15, v54
	s_add_u32 s40, s40, 0x40000
	s_addc_u32 s41, s41, 0
	v_cvt_pk_bf16_f32 v53, v15, v15
	v_lshlrev_b32_e32 v54, 16, v79
	global_store_short v2, v53, s[40:41]
	v_fma_f32 v15, v87, v15, v54
	s_add_u32 s40, s40, 0x40000
	s_addc_u32 s41, s41, 0
	v_cvt_pk_bf16_f32 v50, v15, v15
	v_lshlrev_b32_e32 v54, 16, v80
	global_store_short v2, v50, s[40:41]
	v_fma_f32 v15, v88, v15, v54
	s_add_u32 s40, s40, 0x40000
	s_addc_u32 s41, s41, 0
	v_cvt_pk_bf16_f32 v51, v15, v15
	v_lshlrev_b32_e32 v54, 16, v81
	global_store_short v2, v51, s[40:41]
	v_fma_f32 v15, v89, v15, v54
	s_add_u32 s40, s40, 0x40000
	s_addc_u32 s41, s41, 0
	v_cvt_pk_bf16_f32 v52, v15, v15
	v_lshlrev_b32_e32 v54, 16, v82
	global_store_short v2, v52, s[40:41]
	v_fma_f32 v15, v90, v15, v54
	s_add_u32 s40, s40, 0x40000
	s_addc_u32 s41, s41, 0
	v_cvt_pk_bf16_f32 v53, v15, v15
	v_lshlrev_b32_e32 v54, 16, v83
	global_store_short v2, v53, s[40:41]
	v_fma_f32 v15, v91, v15, v54
	s_add_u32 s40, s40, 0x40000
	s_addc_u32 s41, s41, 0
	global_load_ushort v76, v2, s[98:99]
	global_load_dword v84, v3, s[100:101]
	s_add_u32 s98, s98, 0x40000
	s_addc_u32 s99, s99, 0
	s_add_u32 s100, s100, 0x1000
	s_addc_u32 s101, s101, 0
	global_load_ushort v77, v2, s[98:99]
	global_load_dword v85, v3, s[100:101]
	s_add_u32 s98, s98, 0x40000
	s_addc_u32 s99, s99, 0
	s_add_u32 s100, s100, 0x1000
	s_addc_u32 s101, s101, 0
	global_load_ushort v78, v2, s[98:99]
	global_load_dword v86, v3, s[100:101]
	s_add_u32 s98, s98, 0x40000
	s_addc_u32 s99, s99, 0
	s_add_u32 s100, s100, 0x1000
	s_addc_u32 s101, s101, 0
	global_load_ushort v79, v2, s[98:99]
	global_load_dword v87, v3, s[100:101]
	s_add_u32 s98, s98, 0x40000
	s_addc_u32 s99, s99, 0
	s_add_u32 s100, s100, 0x1000
	s_addc_u32 s101, s101, 0
	global_load_ushort v80, v2, s[98:99]
	global_load_dword v88, v3, s[100:101]
	s_add_u32 s98, s98, 0x40000
	s_addc_u32 s99, s99, 0
	s_add_u32 s100, s100, 0x1000
	s_addc_u32 s101, s101, 0
	global_load_ushort v81, v2, s[98:99]
	global_load_dword v89, v3, s[100:101]
	s_add_u32 s98, s98, 0x40000
	s_addc_u32 s99, s99, 0
	s_add_u32 s100, s100, 0x1000
	s_addc_u32 s101, s101, 0
	global_load_ushort v82, v2, s[98:99]
	global_load_dword v90, v3, s[100:101]
	s_add_u32 s98, s98, 0x40000
	s_addc_u32 s99, s99, 0
	s_add_u32 s100, s100, 0x1000
	s_addc_u32 s101, s101, 0
	global_load_ushort v83, v2, s[98:99]
	global_load_dword v91, v3, s[100:101]
	s_add_u32 s98, s98, 0x40000
	s_addc_u32 s99, s99, 0
	s_add_u32 s100, s100, 0x1000
	s_addc_u32 s101, s101, 0
	s_waitcnt vmcnt(48)
; DI u16 f2bf(float x) { return (u16)(pack2(x, 0.f) & 0xffffu); }
; DI float bf2f(u16 h) { return __uint_as_float(((unsigned)h) << 16); }
; DI void hgrn_scan_phase(const Params& p, char* smem) {
;     ...
;     for (int n0 = 0; n0 < 256; n0 += 8) {
;       float nu[8], nd[8];
;       if (n0 + 8 < 256) {
; #pragma unroll
;         for (int j = 0; j < 8; j++) { nu[j] = bf2f(up[(long)(n0 + 8 + j) * 131072]); nd[j] = dp[(n0 + 8 + j) * 1024]; }
;       } else {
; #pragma unroll
;         for (int j = 0; j < 8; j++) { nu[j] = 0.f; nd[j] = 0.f; }
;       }
; #pragma unroll
;       for (int j = 0; j < 8; j++) { up[(long)(n0 + j) * 131072] = f2bf(S); S = cd[j] * S + cu[j]; }
; #pragma unroll
;       for (int j = 0; j < 8; j++) { cu[j] = nu[j]; cd[j] = nd[j]; }
;     }
	v_cvt_pk_bf16_f32 v50, v15, v15
	v_lshlrev_b32_e32 v54, 16, v92
	global_store_short v2, v50, s[40:41]
	v_fma_f32 v15, v100, v15, v54
	s_add_u32 s40, s40, 0x40000
	s_addc_u32 s41, s41, 0
	v_cvt_pk_bf16_f32 v51, v15, v15
	v_lshlrev_b32_e32 v54, 16, v93
	global_store_short v2, v51, s[40:41]
	v_fma_f32 v15, v101, v15, v54
	s_add_u32 s40, s40, 0x40000
	s_addc_u32 s41, s41, 0
	v_cvt_pk_bf16_f32 v52, v15, v15
	v_lshlrev_b32_e32 v54, 16, v94
	global_store_short v2, v52, s[40:41]
	v_fma_f32 v15, v102, v15, v54
	s_add_u32 s40, s40, 0x40000
	s_addc_u32 s41, s41, 0
	v_cvt_pk_bf16_f32 v53, v15, v15
	v_lshlrev_b32_e32 v54, 16, v95
	global_store_short v2, v53, s[40:41]
	v_fma_f32 v15, v103, v15, v54
	s_add_u32 s40, s40, 0x40000
	s_addc_u32 s41, s41, 0
	v_cvt_pk_bf16_f32 v50, v15, v15
	v_lshlrev_b32_e32 v54, 16, v96
	global_store_short v2, v50, s[40:41]
	v_fma_f32 v15, v104, v15, v54
	s_add_u32 s40, s40, 0x40000
	s_addc_u32 s41, s41, 0
	v_cvt_pk_bf16_f32 v51, v15, v15
	v_lshlrev_b32_e32 v54, 16, v97
	global_store_short v2, v51, s[40:41]
	v_fma_f32 v15, v105, v15, v54
	s_add_u32 s40, s40, 0x40000
	s_addc_u32 s41, s41, 0
	v_cvt_pk_bf16_f32 v52, v15, v15
	v_lshlrev_b32_e32 v54, 16, v98
	global_store_short v2, v52, s[40:41]
	v_fma_f32 v15, v106, v15, v54
	s_add_u32 s40, s40, 0x40000
	s_addc_u32 s41, s41, 0
	v_cvt_pk_bf16_f32 v53, v15, v15
	v_lshlrev_b32_e32 v54, 16, v99
	global_store_short v2, v53, s[40:41]
	v_fma_f32 v15, v107, v15, v54
	s_add_u32 s40, s40, 0x40000
	s_addc_u32 s41, s41, 0
	global_load_ushort v92, v2, s[98:99]
	global_load_dword v100, v3, s[100:101]
	s_add_u32 s98, s98, 0x40000
	s_addc_u32 s99, s99, 0
	s_add_u32 s100, s100, 0x1000
	s_addc_u32 s101, s101, 0
	global_load_ushort v93, v2, s[98:99]
	global_load_dword v101, v3, s[100:101]
	s_add_u32 s98, s98, 0x40000
	s_addc_u32 s99, s99, 0
	s_add_u32 s100, s100, 0x1000
	s_addc_u32 s101, s101, 0
	global_load_ushort v94, v2, s[98:99]
	global_load_dword v102, v3, s[100:101]
	s_add_u32 s98, s98, 0x40000
	s_addc_u32 s99, s99, 0
	s_add_u32 s100, s100, 0x1000
	s_addc_u32 s101, s101, 0
	global_load_ushort v95, v2, s[98:99]
	global_load_dword v103, v3, s[100:101]
	s_add_u32 s98, s98, 0x40000
	s_addc_u32 s99, s99, 0
	s_add_u32 s100, s100, 0x1000
	s_addc_u32 s101, s101, 0
	global_load_ushort v96, v2, s[98:99]
	global_load_dword v104, v3, s[100:101]
	s_add_u32 s98, s98, 0x40000
	s_addc_u32 s99, s99, 0
	s_add_u32 s100, s100, 0x1000
	s_addc_u32 s101, s101, 0
	global_load_ushort v97, v2, s[98:99]
	global_load_dword v105, v3, s[100:101]
	s_add_u32 s98, s98, 0x40000
	s_addc_u32 s99, s99, 0
	s_add_u32 s100, s100, 0x1000
	s_addc_u32 s101, s101, 0
	global_load_ushort v98, v2, s[98:99]
	global_load_dword v106, v3, s[100:101]
	s_add_u32 s98, s98, 0x40000
	s_addc_u32 s99, s99, 0
	s_add_u32 s100, s100, 0x1000
	s_addc_u32 s101, s101, 0
	global_load_ushort v99, v2, s[98:99]
	global_load_dword v107, v3, s[100:101]
	s_add_u32 s98, s98, 0x40000
	s_addc_u32 s99, s99, 0
	s_add_u32 s100, s100, 0x1000
	s_addc_u32 s101, s101, 0
	s_waitcnt vmcnt(48)
	v_cvt_pk_bf16_f32 v50, v15, v15
	v_lshlrev_b32_e32 v54, 16, v60
	global_store_short v2, v50, s[40:41]
	v_fma_f32 v15, v68, v15, v54
	s_add_u32 s40, s40, 0x40000
	s_addc_u32 s41, s41, 0
	v_cvt_pk_bf16_f32 v51, v15, v15
	v_lshlrev_b32_e32 v54, 16, v61
	global_store_short v2, v51, s[40:41]
	v_fma_f32 v15, v69, v15, v54
	s_add_u32 s40, s40, 0x40000
	s_addc_u32 s41, s41, 0
	v_cvt_pk_bf16_f32 v52, v15, v15
	v_lshlrev_b32_e32 v54, 16, v62
	global_store_short v2, v52, s[40:41]
	v_fma_f32 v15, v70, v15, v54
	s_add_u32 s40, s40, 0x40000
	s_addc_u32 s41, s41, 0
	v_cvt_pk_bf16_f32 v53, v15, v15
	v_lshlrev_b32_e32 v54, 16, v63
	global_store_short v2, v53, s[40:41]
	v_fma_f32 v15, v71, v15, v54
	s_add_u32 s40, s40, 0x40000
	s_addc_u32 s41, s41, 0
	v_cvt_pk_bf16_f32 v50, v15, v15
	v_lshlrev_b32_e32 v54, 16, v64
	global_store_short v2, v50, s[40:41]
	v_fma_f32 v15, v72, v15, v54
	s_add_u32 s40, s40, 0x40000
	s_addc_u32 s41, s41, 0
	v_cvt_pk_bf16_f32 v51, v15, v15
	v_lshlrev_b32_e32 v54, 16, v65
	global_store_short v2, v51, s[40:41]
	v_fma_f32 v15, v73, v15, v54
	s_add_u32 s40, s40, 0x40000
	s_addc_u32 s41, s41, 0
	v_cvt_pk_bf16_f32 v52, v15, v15
	v_lshlrev_b32_e32 v54, 16, v66
	global_store_short v2, v52, s[40:41]
	v_fma_f32 v15, v74, v15, v54
	s_add_u32 s40, s40, 0x40000
	s_addc_u32 s41, s41, 0
	v_cvt_pk_bf16_f32 v53, v15, v15
	v_lshlrev_b32_e32 v54, 16, v67
	global_store_short v2, v53, s[40:41]
	v_fma_f32 v15, v75, v15, v54
	s_add_u32 s40, s40, 0x40000
	s_addc_u32 s41, s41, 0
	global_load_ushort v60, v2, s[98:99]
	global_load_dword v68, v3, s[100:101]
	s_add_u32 s98, s98, 0x40000
	s_addc_u32 s99, s99, 0
	s_add_u32 s100, s100, 0x1000
	s_addc_u32 s101, s101, 0
	global_load_ushort v61, v2, s[98:99]
	global_load_dword v69, v3, s[100:101]
	s_add_u32 s98, s98, 0x40000
	s_addc_u32 s99, s99, 0
	s_add_u32 s100, s100, 0x1000
	s_addc_u32 s101, s101, 0
	global_load_ushort v62, v2, s[98:99]
	global_load_dword v70, v3, s[100:101]
	s_add_u32 s98, s98, 0x40000
	s_addc_u32 s99, s99, 0
	s_add_u32 s100, s100, 0x1000
	s_addc_u32 s101, s101, 0
	global_load_ushort v63, v2, s[98:99]
	global_load_dword v71, v3, s[100:101]
	s_add_u32 s98, s98, 0x40000
	s_addc_u32 s99, s99, 0
	s_add_u32 s100, s100, 0x1000
	s_addc_u32 s101, s101, 0
	global_load_ushort v64, v2, s[98:99]
	global_load_dword v72, v3, s[100:101]
	s_add_u32 s98, s98, 0x40000
	s_addc_u32 s99, s99, 0
	s_add_u32 s100, s100, 0x1000
	s_addc_u32 s101, s101, 0
	global_load_ushort v65, v2, s[98:99]
	global_load_dword v73, v3, s[100:101]
	s_add_u32 s98, s98, 0x40000
	s_addc_u32 s99, s99, 0
	s_add_u32 s100, s100, 0x1000
	s_addc_u32 s101, s101, 0
	global_load_ushort v66, v2, s[98:99]
	global_load_dword v74, v3, s[100:101]
	s_add_u32 s98, s98, 0x40000
	s_addc_u32 s99, s99, 0
	s_add_u32 s100, s100, 0x1000
	s_addc_u32 s101, s101, 0
	global_load_ushort v67, v2, s[98:99]
	global_load_dword v75, v3, s[100:101]
	s_add_u32 s98, s98, 0x40000
	s_addc_u32 s99, s99, 0
	s_add_u32 s100, s100, 0x1000
	s_addc_u32 s101, s101, 0
	s_waitcnt vmcnt(48)
; DI u16 f2bf(float x) { return (u16)(pack2(x, 0.f) & 0xffffu); }
; DI float bf2f(u16 h) { return __uint_as_float(((unsigned)h) << 16); }
; DI void hgrn_scan_phase(const Params& p, char* smem) {
;     ...
;     for (int n0 = 0; n0 < 256; n0 += 8) {
;       float nu[8], nd[8];
;       if (n0 + 8 < 256) {
; #pragma unroll
;         for (int j = 0; j < 8; j++) { nu[j] = bf2f(up[(long)(n0 + 8 + j) * 131072]); nd[j] = dp[(n0 + 8 + j) * 1024]; }
;       } else {
; #pragma unroll
;         for (int j = 0; j < 8; j++) { nu[j] = 0.f; nd[j] = 0.f; }
;       }
; #pragma unroll
;       for (int j = 0; j < 8; j++) { up[(long)(n0 + j) * 131072] = f2bf(S); S = cd[j] * S + cu[j]; }
; #pragma unroll
;       for (int j = 0; j < 8; j++) { cu[j] = nu[j]; cd[j] = nd[j]; }
;     }
	v_cvt_pk_bf16_f32 v50, v15, v15
	v_lshlrev_b32_e32 v54, 16, v76
	global_store_short v2, v50, s[40:41]
	v_fma_f32 v15, v84, v15, v54
	s_add_u32 s40, s40, 0x40000
	s_addc_u32 s41, s41, 0
	v_cvt_pk_bf16_f32 v51, v15, v15
	v_lshlrev_b32_e32 v54, 16, v77
	global_store_short v2, v51, s[40:41]
	v_fma_f32 v15, v85, v15, v54
	s_add_u32 s40, s40, 0x40000
	s_addc_u32 s41, s41, 0
	v_cvt_pk_bf16_f32 v52, v15, v15
	v_lshlrev_b32_e32 v54, 16, v78
	global_store_short v2, v52, s[40:41]
	v_fma_f32 v15, v86, v15, v54
	s_add_u32 s40, s40, 0x40000
	s_addc_u32 s41, s41, 0
	v_cvt_pk_bf16_f32 v53, v15, v15
	v_lshlrev_b32_e32 v54, 16, v79
	global_store_short v2, v53, s[40:41]
	v_fma_f32 v15, v87, v15, v54
	s_add_u32 s40, s40, 0x40000
	s_addc_u32 s41, s41, 0
	v_cvt_pk_bf16_f32 v50, v15, v15
	v_lshlrev_b32_e32 v54, 16, v80
	global_store_short v2, v50, s[40:41]
	v_fma_f32 v15, v88, v15, v54
	s_add_u32 s40, s40, 0x40000
	s_addc_u32 s41, s41, 0
	v_cvt_pk_bf16_f32 v51, v15, v15
	v_lshlrev_b32_e32 v54, 16, v81
	global_store_short v2, v51, s[40:41]
	v_fma_f32 v15, v89, v15, v54
	s_add_u32 s40, s40, 0x40000
	s_addc_u32 s41, s41, 0
	v_cvt_pk_bf16_f32 v52, v15, v15
	v_lshlrev_b32_e32 v54, 16, v82
	global_store_short v2, v52, s[40:41]
	v_fma_f32 v15, v90, v15, v54
	s_add_u32 s40, s40, 0x40000
	s_addc_u32 s41, s41, 0
	v_cvt_pk_bf16_f32 v53, v15, v15
	v_lshlrev_b32_e32 v54, 16, v83
	global_store_short v2, v53, s[40:41]
	v_fma_f32 v15, v91, v15, v54
	s_add_u32 s40, s40, 0x40000
	s_addc_u32 s41, s41, 0
	global_load_ushort v76, v2, s[98:99]
	global_load_dword v84, v3, s[100:101]
	s_add_u32 s98, s98, 0x40000
	s_addc_u32 s99, s99, 0
	s_add_u32 s100, s100, 0x1000
	s_addc_u32 s101, s101, 0
	global_load_ushort v77, v2, s[98:99]
	global_load_dword v85, v3, s[100:101]
	s_add_u32 s98, s98, 0x40000
	s_addc_u32 s99, s99, 0
	s_add_u32 s100, s100, 0x1000
	s_addc_u32 s101, s101, 0
	global_load_ushort v78, v2, s[98:99]
	global_load_dword v86, v3, s[100:101]
	s_add_u32 s98, s98, 0x40000
	s_addc_u32 s99, s99, 0
	s_add_u32 s100, s100, 0x1000
	s_addc_u32 s101, s101, 0
	global_load_ushort v79, v2, s[98:99]
	global_load_dword v87, v3, s[100:101]
	s_add_u32 s98, s98, 0x40000
	s_addc_u32 s99, s99, 0
	s_add_u32 s100, s100, 0x1000
	s_addc_u32 s101, s101, 0
	global_load_ushort v80, v2, s[98:99]
	global_load_dword v88, v3, s[100:101]
	s_add_u32 s98, s98, 0x40000
	s_addc_u32 s99, s99, 0
	s_add_u32 s100, s100, 0x1000
	s_addc_u32 s101, s101, 0
	global_load_ushort v81, v2, s[98:99]
	global_load_dword v89, v3, s[100:101]
	s_add_u32 s98, s98, 0x40000
	s_addc_u32 s99, s99, 0
	s_add_u32 s100, s100, 0x1000
	s_addc_u32 s101, s101, 0
	global_load_ushort v82, v2, s[98:99]
	global_load_dword v90, v3, s[100:101]
	s_add_u32 s98, s98, 0x40000
	s_addc_u32 s99, s99, 0
	s_add_u32 s100, s100, 0x1000
	s_addc_u32 s101, s101, 0
	global_load_ushort v83, v2, s[98:99]
	global_load_dword v91, v3, s[100:101]
	s_add_u32 s98, s98, 0x40000
	s_addc_u32 s99, s99, 0
	s_add_u32 s100, s100, 0x1000
	s_addc_u32 s101, s101, 0
	s_waitcnt vmcnt(48)
	v_cvt_pk_bf16_f32 v50, v15, v15
	v_lshlrev_b32_e32 v54, 16, v92
	global_store_short v2, v50, s[40:41]
	v_fma_f32 v15, v100, v15, v54
	s_add_u32 s40, s40, 0x40000
	s_addc_u32 s41, s41, 0
	v_cvt_pk_bf16_f32 v51, v15, v15
	v_lshlrev_b32_e32 v54, 16, v93
	global_store_short v2, v51, s[40:41]
	v_fma_f32 v15, v101, v15, v54
	s_add_u32 s40, s40, 0x40000
	s_addc_u32 s41, s41, 0
	v_cvt_pk_bf16_f32 v52, v15, v15
	v_lshlrev_b32_e32 v54, 16, v94
	global_store_short v2, v52, s[40:41]
	v_fma_f32 v15, v102, v15, v54
	s_add_u32 s40, s40, 0x40000
	s_addc_u32 s41, s41, 0
	v_cvt_pk_bf16_f32 v53, v15, v15
	v_lshlrev_b32_e32 v54, 16, v95
	global_store_short v2, v53, s[40:41]
	v_fma_f32 v15, v103, v15, v54
	s_add_u32 s40, s40, 0x40000
	s_addc_u32 s41, s41, 0
	v_cvt_pk_bf16_f32 v50, v15, v15
	v_lshlrev_b32_e32 v54, 16, v96
	global_store_short v2, v50, s[40:41]
	v_fma_f32 v15, v104, v15, v54
	s_add_u32 s40, s40, 0x40000
	s_addc_u32 s41, s41, 0
	v_cvt_pk_bf16_f32 v51, v15, v15
	v_lshlrev_b32_e32 v54, 16, v97
	global_store_short v2, v51, s[40:41]
	v_fma_f32 v15, v105, v15, v54
	s_add_u32 s40, s40, 0x40000
	s_addc_u32 s41, s41, 0
	v_cvt_pk_bf16_f32 v52, v15, v15
	v_lshlrev_b32_e32 v54, 16, v98
	global_store_short v2, v52, s[40:41]
	v_fma_f32 v15, v106, v15, v54
	s_add_u32 s40, s40, 0x40000
	s_addc_u32 s41, s41, 0
	v_cvt_pk_bf16_f32 v53, v15, v15
	v_lshlrev_b32_e32 v54, 16, v99
	global_store_short v2, v53, s[40:41]
	v_fma_f32 v15, v107, v15, v54
	s_add_u32 s40, s40, 0x40000
	s_addc_u32 s41, s41, 0
	global_load_ushort v92, v2, s[98:99]
	global_load_dword v100, v3, s[100:101]
	s_add_u32 s98, s98, 0x40000
	s_addc_u32 s99, s99, 0
	s_add_u32 s100, s100, 0x1000
	s_addc_u32 s101, s101, 0
	global_load_ushort v93, v2, s[98:99]
	global_load_dword v101, v3, s[100:101]
	s_add_u32 s98, s98, 0x40000
	s_addc_u32 s99, s99, 0
	s_add_u32 s100, s100, 0x1000
	s_addc_u32 s101, s101, 0
	global_load_ushort v94, v2, s[98:99]
	global_load_dword v102, v3, s[100:101]
	s_add_u32 s98, s98, 0x40000
	s_addc_u32 s99, s99, 0
	s_add_u32 s100, s100, 0x1000
	s_addc_u32 s101, s101, 0
	global_load_ushort v95, v2, s[98:99]
	global_load_dword v103, v3, s[100:101]
	s_add_u32 s98, s98, 0x40000
	s_addc_u32 s99, s99, 0
	s_add_u32 s100, s100, 0x1000
	s_addc_u32 s101, s101, 0
	global_load_ushort v96, v2, s[98:99]
	global_load_dword v104, v3, s[100:101]
	s_add_u32 s98, s98, 0x40000
	s_addc_u32 s99, s99, 0
	s_add_u32 s100, s100, 0x1000
	s_addc_u32 s101, s101, 0
	global_load_ushort v97, v2, s[98:99]
	global_load_dword v105, v3, s[100:101]
	s_add_u32 s98, s98, 0x40000
	s_addc_u32 s99, s99, 0
	s_add_u32 s100, s100, 0x1000
	s_addc_u32 s101, s101, 0
	global_load_ushort v98, v2, s[98:99]
	global_load_dword v106, v3, s[100:101]
	s_add_u32 s98, s98, 0x40000
	s_addc_u32 s99, s99, 0
	s_add_u32 s100, s100, 0x1000
	s_addc_u32 s101, s101, 0
	global_load_ushort v99, v2, s[98:99]
	global_load_dword v107, v3, s[100:101]
	s_add_u32 s98, s98, 0x40000
	s_addc_u32 s99, s99, 0
	s_add_u32 s100, s100, 0x1000
	s_addc_u32 s101, s101, 0
	s_waitcnt vmcnt(48)
; DI u16 f2bf(float x) { return (u16)(pack2(x, 0.f) & 0xffffu); }
; DI float bf2f(u16 h) { return __uint_as_float(((unsigned)h) << 16); }
; DI void hgrn_scan_phase(const Params& p, char* smem) {
;     ...
;     for (int n0 = 0; n0 < 256; n0 += 8) {
;       float nu[8], nd[8];
;       if (n0 + 8 < 256) {
; #pragma unroll
;         for (int j = 0; j < 8; j++) { nu[j] = bf2f(up[(long)(n0 + 8 + j) * 131072]); nd[j] = dp[(n0 + 8 + j) * 1024]; }
;       } else {
; #pragma unroll
;         for (int j = 0; j < 8; j++) { nu[j] = 0.f; nd[j] = 0.f; }
;       }
; #pragma unroll
;       for (int j = 0; j < 8; j++) { up[(long)(n0 + j) * 131072] = f2bf(S); S = cd[j] * S + cu[j]; }
; #pragma unroll
;       for (int j = 0; j < 8; j++) { cu[j] = nu[j]; cd[j] = nd[j]; }
;     }
	v_cvt_pk_bf16_f32 v50, v15, v15
	v_lshlrev_b32_e32 v54, 16, v60
	global_store_short v2, v50, s[40:41]
	v_fma_f32 v15, v68, v15, v54
	s_add_u32 s40, s40, 0x40000
	s_addc_u32 s41, s41, 0
	v_cvt_pk_bf16_f32 v51, v15, v15
	v_lshlrev_b32_e32 v54, 16, v61
	global_store_short v2, v51, s[40:41]
	v_fma_f32 v15, v69, v15, v54
	s_add_u32 s40, s40, 0x40000
	s_addc_u32 s41, s41, 0
	v_cvt_pk_bf16_f32 v52, v15, v15
	v_lshlrev_b32_e32 v54, 16, v62
	global_store_short v2, v52, s[40:41]
	v_fma_f32 v15, v70, v15, v54
	s_add_u32 s40, s40, 0x40000
	s_addc_u32 s41, s41, 0
	v_cvt_pk_bf16_f32 v53, v15, v15
	v_lshlrev_b32_e32 v54, 16, v63
	global_store_short v2, v53, s[40:41]
	v_fma_f32 v15, v71, v15, v54
	s_add_u32 s40, s40, 0x40000
	s_addc_u32 s41, s41, 0
	v_cvt_pk_bf16_f32 v50, v15, v15
	v_lshlrev_b32_e32 v54, 16, v64
	global_store_short v2, v50, s[40:41]
	v_fma_f32 v15, v72, v15, v54
	s_add_u32 s40, s40, 0x40000
	s_addc_u32 s41, s41, 0
	v_cvt_pk_bf16_f32 v51, v15, v15
	v_lshlrev_b32_e32 v54, 16, v65
	global_store_short v2, v51, s[40:41]
	v_fma_f32 v15, v73, v15, v54
	s_add_u32 s40, s40, 0x40000
	s_addc_u32 s41, s41, 0
	v_cvt_pk_bf16_f32 v52, v15, v15
	v_lshlrev_b32_e32 v54, 16, v66
	global_store_short v2, v52, s[40:41]
	v_fma_f32 v15, v74, v15, v54
	s_add_u32 s40, s40, 0x40000
	s_addc_u32 s41, s41, 0
	v_cvt_pk_bf16_f32 v53, v15, v15
	v_lshlrev_b32_e32 v54, 16, v67
	global_store_short v2, v53, s[40:41]
	v_fma_f32 v15, v75, v15, v54
	s_add_u32 s40, s40, 0x40000
	s_addc_u32 s41, s41, 0
	global_load_ushort v60, v2, s[98:99]
	global_load_dword v68, v3, s[100:101]
	s_add_u32 s98, s98, 0x40000
	s_addc_u32 s99, s99, 0
	s_add_u32 s100, s100, 0x1000
	s_addc_u32 s101, s101, 0
	global_load_ushort v61, v2, s[98:99]
	global_load_dword v69, v3, s[100:101]
	s_add_u32 s98, s98, 0x40000
	s_addc_u32 s99, s99, 0
	s_add_u32 s100, s100, 0x1000
	s_addc_u32 s101, s101, 0
	global_load_ushort v62, v2, s[98:99]
	global_load_dword v70, v3, s[100:101]
	s_add_u32 s98, s98, 0x40000
	s_addc_u32 s99, s99, 0
	s_add_u32 s100, s100, 0x1000
	s_addc_u32 s101, s101, 0
	global_load_ushort v63, v2, s[98:99]
	global_load_dword v71, v3, s[100:101]
	s_add_u32 s98, s98, 0x40000
	s_addc_u32 s99, s99, 0
	s_add_u32 s100, s100, 0x1000
	s_addc_u32 s101, s101, 0
	global_load_ushort v64, v2, s[98:99]
	global_load_dword v72, v3, s[100:101]
	s_add_u32 s98, s98, 0x40000
	s_addc_u32 s99, s99, 0
	s_add_u32 s100, s100, 0x1000
	s_addc_u32 s101, s101, 0
	global_load_ushort v65, v2, s[98:99]
	global_load_dword v73, v3, s[100:101]
	s_add_u32 s98, s98, 0x40000
	s_addc_u32 s99, s99, 0
	s_add_u32 s100, s100, 0x1000
	s_addc_u32 s101, s101, 0
	global_load_ushort v66, v2, s[98:99]
	global_load_dword v74, v3, s[100:101]
	s_add_u32 s98, s98, 0x40000
	s_addc_u32 s99, s99, 0
	s_add_u32 s100, s100, 0x1000
	s_addc_u32 s101, s101, 0
	global_load_ushort v67, v2, s[98:99]
	global_load_dword v75, v3, s[100:101]
	s_add_u32 s98, s98, 0x40000
	s_addc_u32 s99, s99, 0
	s_add_u32 s100, s100, 0x1000
	s_addc_u32 s101, s101, 0
	s_waitcnt vmcnt(48)
	v_cvt_pk_bf16_f32 v50, v15, v15
	v_lshlrev_b32_e32 v54, 16, v76
	global_store_short v2, v50, s[40:41]
	v_fma_f32 v15, v84, v15, v54
	s_add_u32 s40, s40, 0x40000
	s_addc_u32 s41, s41, 0
	v_cvt_pk_bf16_f32 v51, v15, v15
	v_lshlrev_b32_e32 v54, 16, v77
	global_store_short v2, v51, s[40:41]
	v_fma_f32 v15, v85, v15, v54
	s_add_u32 s40, s40, 0x40000
	s_addc_u32 s41, s41, 0
	v_cvt_pk_bf16_f32 v52, v15, v15
	v_lshlrev_b32_e32 v54, 16, v78
	global_store_short v2, v52, s[40:41]
	v_fma_f32 v15, v86, v15, v54
	s_add_u32 s40, s40, 0x40000
	s_addc_u32 s41, s41, 0
	v_cvt_pk_bf16_f32 v53, v15, v15
	v_lshlrev_b32_e32 v54, 16, v79
	global_store_short v2, v53, s[40:41]
	v_fma_f32 v15, v87, v15, v54
	s_add_u32 s40, s40, 0x40000
	s_addc_u32 s41, s41, 0
	v_cvt_pk_bf16_f32 v50, v15, v15
	v_lshlrev_b32_e32 v54, 16, v80
	global_store_short v2, v50, s[40:41]
	v_fma_f32 v15, v88, v15, v54
	s_add_u32 s40, s40, 0x40000
	s_addc_u32 s41, s41, 0
	v_cvt_pk_bf16_f32 v51, v15, v15
	v_lshlrev_b32_e32 v54, 16, v81
	global_store_short v2, v51, s[40:41]
	v_fma_f32 v15, v89, v15, v54
	s_add_u32 s40, s40, 0x40000
	s_addc_u32 s41, s41, 0
	v_cvt_pk_bf16_f32 v52, v15, v15
	v_lshlrev_b32_e32 v54, 16, v82
	global_store_short v2, v52, s[40:41]
	v_fma_f32 v15, v90, v15, v54
	s_add_u32 s40, s40, 0x40000
	s_addc_u32 s41, s41, 0
	v_cvt_pk_bf16_f32 v53, v15, v15
	v_lshlrev_b32_e32 v54, 16, v83
	global_store_short v2, v53, s[40:41]
	v_fma_f32 v15, v91, v15, v54
	s_add_u32 s40, s40, 0x40000
	s_addc_u32 s41, s41, 0
	global_load_ushort v76, v2, s[98:99]
	global_load_dword v84, v3, s[100:101]
	s_add_u32 s98, s98, 0x40000
	s_addc_u32 s99, s99, 0
	s_add_u32 s100, s100, 0x1000
	s_addc_u32 s101, s101, 0
	global_load_ushort v77, v2, s[98:99]
	global_load_dword v85, v3, s[100:101]
	s_add_u32 s98, s98, 0x40000
	s_addc_u32 s99, s99, 0
	s_add_u32 s100, s100, 0x1000
	s_addc_u32 s101, s101, 0
	global_load_ushort v78, v2, s[98:99]
	global_load_dword v86, v3, s[100:101]
	s_add_u32 s98, s98, 0x40000
	s_addc_u32 s99, s99, 0
	s_add_u32 s100, s100, 0x1000
	s_addc_u32 s101, s101, 0
	global_load_ushort v79, v2, s[98:99]
	global_load_dword v87, v3, s[100:101]
	s_add_u32 s98, s98, 0x40000
	s_addc_u32 s99, s99, 0
	s_add_u32 s100, s100, 0x1000
	s_addc_u32 s101, s101, 0
	global_load_ushort v80, v2, s[98:99]
	global_load_dword v88, v3, s[100:101]
	s_add_u32 s98, s98, 0x40000
	s_addc_u32 s99, s99, 0
	s_add_u32 s100, s100, 0x1000
	s_addc_u32 s101, s101, 0
	global_load_ushort v81, v2, s[98:99]
	global_load_dword v89, v3, s[100:101]
	s_add_u32 s98, s98, 0x40000
	s_addc_u32 s99, s99, 0
	s_add_u32 s100, s100, 0x1000
	s_addc_u32 s101, s101, 0
	global_load_ushort v82, v2, s[98:99]
	global_load_dword v90, v3, s[100:101]
	s_add_u32 s98, s98, 0x40000
	s_addc_u32 s99, s99, 0
	s_add_u32 s100, s100, 0x1000
	s_addc_u32 s101, s101, 0
	global_load_ushort v83, v2, s[98:99]
	global_load_dword v91, v3, s[100:101]
	s_add_u32 s98, s98, 0x40000
	s_addc_u32 s99, s99, 0
	s_add_u32 s100, s100, 0x1000
	s_addc_u32 s101, s101, 0
	s_waitcnt vmcnt(48)
; DI u16 f2bf(float x) { return (u16)(pack2(x, 0.f) & 0xffffu); }
; DI float bf2f(u16 h) { return __uint_as_float(((unsigned)h) << 16); }
; DI void hgrn_scan_phase(const Params& p, char* smem) {
;     ...
;     for (int n0 = 0; n0 < 256; n0 += 8) {
;       float nu[8], nd[8];
;       if (n0 + 8 < 256) {
; #pragma unroll
;         for (int j = 0; j < 8; j++) { nu[j] = bf2f(up[(long)(n0 + 8 + j) * 131072]); nd[j] = dp[(n0 + 8 + j) * 1024]; }
;       } else {
; #pragma unroll
;         for (int j = 0; j < 8; j++) { nu[j] = 0.f; nd[j] = 0.f; }
;       }
; #pragma unroll
;       for (int j = 0; j < 8; j++) { up[(long)(n0 + j) * 131072] = f2bf(S); S = cd[j] * S + cu[j]; }
; #pragma unroll
;       for (int j = 0; j < 8; j++) { cu[j] = nu[j]; cd[j] = nd[j]; }
;     }
	v_cvt_pk_bf16_f32 v50, v15, v15
	v_lshlrev_b32_e32 v54, 16, v92
	global_store_short v2, v50, s[40:41]
	v_fma_f32 v15, v100, v15, v54
	s_add_u32 s40, s40, 0x40000
	s_addc_u32 s41, s41, 0
	v_cvt_pk_bf16_f32 v51, v15, v15
	v_lshlrev_b32_e32 v54, 16, v93
	global_store_short v2, v51, s[40:41]
	v_fma_f32 v15, v101, v15, v54
	s_add_u32 s40, s40, 0x40000
	s_addc_u32 s41, s41, 0
	v_cvt_pk_bf16_f32 v52, v15, v15
	v_lshlrev_b32_e32 v54, 16, v94
	global_store_short v2, v52, s[40:41]
	v_fma_f32 v15, v102, v15, v54
	s_add_u32 s40, s40, 0x40000
	s_addc_u32 s41, s41, 0
	v_cvt_pk_bf16_f32 v53, v15, v15
	v_lshlrev_b32_e32 v54, 16, v95
	global_store_short v2, v53, s[40:41]
	v_fma_f32 v15, v103, v15, v54
	s_add_u32 s40, s40, 0x40000
	s_addc_u32 s41, s41, 0
	v_cvt_pk_bf16_f32 v50, v15, v15
	v_lshlrev_b32_e32 v54, 16, v96
	global_store_short v2, v50, s[40:41]
	v_fma_f32 v15, v104, v15, v54
	s_add_u32 s40, s40, 0x40000
	s_addc_u32 s41, s41, 0
	v_cvt_pk_bf16_f32 v51, v15, v15
	v_lshlrev_b32_e32 v54, 16, v97
	global_store_short v2, v51, s[40:41]
	v_fma_f32 v15, v105, v15, v54
	s_add_u32 s40, s40, 0x40000
	s_addc_u32 s41, s41, 0
	v_cvt_pk_bf16_f32 v52, v15, v15
	v_lshlrev_b32_e32 v54, 16, v98
	global_store_short v2, v52, s[40:41]
	v_fma_f32 v15, v106, v15, v54
	s_add_u32 s40, s40, 0x40000
	s_addc_u32 s41, s41, 0
	v_cvt_pk_bf16_f32 v53, v15, v15
	v_lshlrev_b32_e32 v54, 16, v99
	global_store_short v2, v53, s[40:41]
	v_fma_f32 v15, v107, v15, v54
	s_add_u32 s40, s40, 0x40000
	s_addc_u32 s41, s41, 0
	global_load_ushort v92, v2, s[98:99]
	global_load_dword v100, v3, s[100:101]
	s_add_u32 s98, s98, 0x40000
	s_addc_u32 s99, s99, 0
	s_add_u32 s100, s100, 0x1000
	s_addc_u32 s101, s101, 0
	global_load_ushort v93, v2, s[98:99]
	global_load_dword v101, v3, s[100:101]
	s_add_u32 s98, s98, 0x40000
	s_addc_u32 s99, s99, 0
	s_add_u32 s100, s100, 0x1000
	s_addc_u32 s101, s101, 0
	global_load_ushort v94, v2, s[98:99]
	global_load_dword v102, v3, s[100:101]
	s_add_u32 s98, s98, 0x40000
	s_addc_u32 s99, s99, 0
	s_add_u32 s100, s100, 0x1000
	s_addc_u32 s101, s101, 0
	global_load_ushort v95, v2, s[98:99]
	global_load_dword v103, v3, s[100:101]
	s_add_u32 s98, s98, 0x40000
	s_addc_u32 s99, s99, 0
	s_add_u32 s100, s100, 0x1000
	s_addc_u32 s101, s101, 0
	global_load_ushort v96, v2, s[98:99]
	global_load_dword v104, v3, s[100:101]
	s_add_u32 s98, s98, 0x40000
	s_addc_u32 s99, s99, 0
	s_add_u32 s100, s100, 0x1000
	s_addc_u32 s101, s101, 0
	global_load_ushort v97, v2, s[98:99]
	global_load_dword v105, v3, s[100:101]
	s_add_u32 s98, s98, 0x40000
	s_addc_u32 s99, s99, 0
	s_add_u32 s100, s100, 0x1000
	s_addc_u32 s101, s101, 0
	global_load_ushort v98, v2, s[98:99]
	global_load_dword v106, v3, s[100:101]
	s_add_u32 s98, s98, 0x40000
	s_addc_u32 s99, s99, 0
	s_add_u32 s100, s100, 0x1000
	s_addc_u32 s101, s101, 0
	global_load_ushort v99, v2, s[98:99]
	global_load_dword v107, v3, s[100:101]
	s_add_u32 s98, s98, 0x40000
	s_addc_u32 s99, s99, 0
	s_add_u32 s100, s100, 0x1000
	s_addc_u32 s101, s101, 0
	s_waitcnt vmcnt(48)
	v_cvt_pk_bf16_f32 v50, v15, v15
	v_lshlrev_b32_e32 v54, 16, v60
	global_store_short v2, v50, s[40:41]
	v_fma_f32 v15, v68, v15, v54
	s_add_u32 s40, s40, 0x40000
	s_addc_u32 s41, s41, 0
	v_cvt_pk_bf16_f32 v51, v15, v15
	v_lshlrev_b32_e32 v54, 16, v61
	global_store_short v2, v51, s[40:41]
	v_fma_f32 v15, v69, v15, v54
	s_add_u32 s40, s40, 0x40000
	s_addc_u32 s41, s41, 0
	v_cvt_pk_bf16_f32 v52, v15, v15
	v_lshlrev_b32_e32 v54, 16, v62
	global_store_short v2, v52, s[40:41]
	v_fma_f32 v15, v70, v15, v54
	s_add_u32 s40, s40, 0x40000
	s_addc_u32 s41, s41, 0
	v_cvt_pk_bf16_f32 v53, v15, v15
	v_lshlrev_b32_e32 v54, 16, v63
	global_store_short v2, v53, s[40:41]
	v_fma_f32 v15, v71, v15, v54
	s_add_u32 s40, s40, 0x40000
	s_addc_u32 s41, s41, 0
	v_cvt_pk_bf16_f32 v50, v15, v15
	v_lshlrev_b32_e32 v54, 16, v64
	global_store_short v2, v50, s[40:41]
	v_fma_f32 v15, v72, v15, v54
	s_add_u32 s40, s40, 0x40000
	s_addc_u32 s41, s41, 0
	v_cvt_pk_bf16_f32 v51, v15, v15
	v_lshlrev_b32_e32 v54, 16, v65
	global_store_short v2, v51, s[40:41]
	v_fma_f32 v15, v73, v15, v54
	s_add_u32 s40, s40, 0x40000
	s_addc_u32 s41, s41, 0
	v_cvt_pk_bf16_f32 v52, v15, v15
	v_lshlrev_b32_e32 v54, 16, v66
	global_store_short v2, v52, s[40:41]
	v_fma_f32 v15, v74, v15, v54
	s_add_u32 s40, s40, 0x40000
	s_addc_u32 s41, s41, 0
	v_cvt_pk_bf16_f32 v53, v15, v15
	v_lshlrev_b32_e32 v54, 16, v67
	global_store_short v2, v53, s[40:41]
	v_fma_f32 v15, v75, v15, v54
	s_add_u32 s40, s40, 0x40000
	s_addc_u32 s41, s41, 0
	global_load_ushort v60, v2, s[98:99]
	global_load_dword v68, v3, s[100:101]
	s_add_u32 s98, s98, 0x40000
	s_addc_u32 s99, s99, 0
	s_add_u32 s100, s100, 0x1000
	s_addc_u32 s101, s101, 0
	global_load_ushort v61, v2, s[98:99]
	global_load_dword v69, v3, s[100:101]
	s_add_u32 s98, s98, 0x40000
	s_addc_u32 s99, s99, 0
	s_add_u32 s100, s100, 0x1000
	s_addc_u32 s101, s101, 0
	global_load_ushort v62, v2, s[98:99]
	global_load_dword v70, v3, s[100:101]
	s_add_u32 s98, s98, 0x40000
	s_addc_u32 s99, s99, 0
	s_add_u32 s100, s100, 0x1000
	s_addc_u32 s101, s101, 0
	global_load_ushort v63, v2, s[98:99]
	global_load_dword v71, v3, s[100:101]
	s_add_u32 s98, s98, 0x40000
	s_addc_u32 s99, s99, 0
	s_add_u32 s100, s100, 0x1000
	s_addc_u32 s101, s101, 0
	global_load_ushort v64, v2, s[98:99]
	global_load_dword v72, v3, s[100:101]
	s_add_u32 s98, s98, 0x40000
	s_addc_u32 s99, s99, 0
	s_add_u32 s100, s100, 0x1000
	s_addc_u32 s101, s101, 0
	global_load_ushort v65, v2, s[98:99]
	global_load_dword v73, v3, s[100:101]
	s_add_u32 s98, s98, 0x40000
	s_addc_u32 s99, s99, 0
	s_add_u32 s100, s100, 0x1000
	s_addc_u32 s101, s101, 0
	global_load_ushort v66, v2, s[98:99]
	global_load_dword v74, v3, s[100:101]
	s_add_u32 s98, s98, 0x40000
	s_addc_u32 s99, s99, 0
	s_add_u32 s100, s100, 0x1000
	s_addc_u32 s101, s101, 0
	global_load_ushort v67, v2, s[98:99]
	global_load_dword v75, v3, s[100:101]
	s_add_u32 s98, s98, 0x40000
	s_addc_u32 s99, s99, 0
	s_add_u32 s100, s100, 0x1000
	s_addc_u32 s101, s101, 0
	s_waitcnt vmcnt(48)
; DI u16 f2bf(float x) { return (u16)(pack2(x, 0.f) & 0xffffu); }
; DI float bf2f(u16 h) { return __uint_as_float(((unsigned)h) << 16); }
; DI void hgrn_scan_phase(const Params& p, char* smem) {
;     ...
;     for (int n0 = 0; n0 < 256; n0 += 8) {
;       float nu[8], nd[8];
;       if (n0 + 8 < 256) {
; #pragma unroll
;         for (int j = 0; j < 8; j++) { nu[j] = bf2f(up[(long)(n0 + 8 + j) * 131072]); nd[j] = dp[(n0 + 8 + j) * 1024]; }
;       } else {
; #pragma unroll
;         for (int j = 0; j < 8; j++) { nu[j] = 0.f; nd[j] = 0.f; }
;       }
; #pragma unroll
;       for (int j = 0; j < 8; j++) { up[(long)(n0 + j) * 131072] = f2bf(S); S = cd[j] * S + cu[j]; }
; #pragma unroll
;       for (int j = 0; j < 8; j++) { cu[j] = nu[j]; cd[j] = nd[j]; }
;     }
	v_cvt_pk_bf16_f32 v50, v15, v15
	v_lshlrev_b32_e32 v54, 16, v76
	global_store_short v2, v50, s[40:41]
	v_fma_f32 v15, v84, v15, v54
	s_add_u32 s40, s40, 0x40000
	s_addc_u32 s41, s41, 0
	v_cvt_pk_bf16_f32 v51, v15, v15
	v_lshlrev_b32_e32 v54, 16, v77
	global_store_short v2, v51, s[40:41]
	v_fma_f32 v15, v85, v15, v54
	s_add_u32 s40, s40, 0x40000
	s_addc_u32 s41, s41, 0
	v_cvt_pk_bf16_f32 v52, v15, v15
	v_lshlrev_b32_e32 v54, 16, v78
	global_store_short v2, v52, s[40:41]
	v_fma_f32 v15, v86, v15, v54
	s_add_u32 s40, s40, 0x40000
	s_addc_u32 s41, s41, 0
	v_cvt_pk_bf16_f32 v53, v15, v15
	v_lshlrev_b32_e32 v54, 16, v79
	global_store_short v2, v53, s[40:41]
	v_fma_f32 v15, v87, v15, v54
	s_add_u32 s40, s40, 0x40000
	s_addc_u32 s41, s41, 0
	v_cvt_pk_bf16_f32 v50, v15, v15
	v_lshlrev_b32_e32 v54, 16, v80
	global_store_short v2, v50, s[40:41]
	v_fma_f32 v15, v88, v15, v54
	s_add_u32 s40, s40, 0x40000
	s_addc_u32 s41, s41, 0
	v_cvt_pk_bf16_f32 v51, v15, v15
	v_lshlrev_b32_e32 v54, 16, v81
	global_store_short v2, v51, s[40:41]
	v_fma_f32 v15, v89, v15, v54
	s_add_u32 s40, s40, 0x40000
	s_addc_u32 s41, s41, 0
	v_cvt_pk_bf16_f32 v52, v15, v15
	v_lshlrev_b32_e32 v54, 16, v82
	global_store_short v2, v52, s[40:41]
	v_fma_f32 v15, v90, v15, v54
	s_add_u32 s40, s40, 0x40000
	s_addc_u32 s41, s41, 0
	v_cvt_pk_bf16_f32 v53, v15, v15
	v_lshlrev_b32_e32 v54, 16, v83
	global_store_short v2, v53, s[40:41]
	v_fma_f32 v15, v91, v15, v54
	s_add_u32 s40, s40, 0x40000
	s_addc_u32 s41, s41, 0
	global_load_ushort v76, v2, s[98:99]
	global_load_dword v84, v3, s[100:101]
	s_add_u32 s98, s98, 0x40000
	s_addc_u32 s99, s99, 0
	s_add_u32 s100, s100, 0x1000
	s_addc_u32 s101, s101, 0
	global_load_ushort v77, v2, s[98:99]
	global_load_dword v85, v3, s[100:101]
	s_add_u32 s98, s98, 0x40000
	s_addc_u32 s99, s99, 0
	s_add_u32 s100, s100, 0x1000
	s_addc_u32 s101, s101, 0
	global_load_ushort v78, v2, s[98:99]
	global_load_dword v86, v3, s[100:101]
	s_add_u32 s98, s98, 0x40000
	s_addc_u32 s99, s99, 0
	s_add_u32 s100, s100, 0x1000
	s_addc_u32 s101, s101, 0
	global_load_ushort v79, v2, s[98:99]
	global_load_dword v87, v3, s[100:101]
	s_add_u32 s98, s98, 0x40000
	s_addc_u32 s99, s99, 0
	s_add_u32 s100, s100, 0x1000
	s_addc_u32 s101, s101, 0
	global_load_ushort v80, v2, s[98:99]
	global_load_dword v88, v3, s[100:101]
	s_add_u32 s98, s98, 0x40000
	s_addc_u32 s99, s99, 0
	s_add_u32 s100, s100, 0x1000
	s_addc_u32 s101, s101, 0
	global_load_ushort v81, v2, s[98:99]
	global_load_dword v89, v3, s[100:101]
	s_add_u32 s98, s98, 0x40000
	s_addc_u32 s99, s99, 0
	s_add_u32 s100, s100, 0x1000
	s_addc_u32 s101, s101, 0
	global_load_ushort v82, v2, s[98:99]
	global_load_dword v90, v3, s[100:101]
	s_add_u32 s98, s98, 0x40000
	s_addc_u32 s99, s99, 0
	s_add_u32 s100, s100, 0x1000
	s_addc_u32 s101, s101, 0
	global_load_ushort v83, v2, s[98:99]
	global_load_dword v91, v3, s[100:101]
	s_add_u32 s98, s98, 0x40000
	s_addc_u32 s99, s99, 0
	s_add_u32 s100, s100, 0x1000
	s_addc_u32 s101, s101, 0
	s_waitcnt vmcnt(48)
	v_cvt_pk_bf16_f32 v50, v15, v15
	v_lshlrev_b32_e32 v54, 16, v92
	global_store_short v2, v50, s[40:41]
	v_fma_f32 v15, v100, v15, v54
	s_add_u32 s40, s40, 0x40000
	s_addc_u32 s41, s41, 0
	v_cvt_pk_bf16_f32 v51, v15, v15
	v_lshlrev_b32_e32 v54, 16, v93
	global_store_short v2, v51, s[40:41]
	v_fma_f32 v15, v101, v15, v54
	s_add_u32 s40, s40, 0x40000
	s_addc_u32 s41, s41, 0
	v_cvt_pk_bf16_f32 v52, v15, v15
	v_lshlrev_b32_e32 v54, 16, v94
	global_store_short v2, v52, s[40:41]
	v_fma_f32 v15, v102, v15, v54
	s_add_u32 s40, s40, 0x40000
	s_addc_u32 s41, s41, 0
	v_cvt_pk_bf16_f32 v53, v15, v15
	v_lshlrev_b32_e32 v54, 16, v95
	global_store_short v2, v53, s[40:41]
	v_fma_f32 v15, v103, v15, v54
	s_add_u32 s40, s40, 0x40000
	s_addc_u32 s41, s41, 0
	v_cvt_pk_bf16_f32 v50, v15, v15
	v_lshlrev_b32_e32 v54, 16, v96
	global_store_short v2, v50, s[40:41]
	v_fma_f32 v15, v104, v15, v54
	s_add_u32 s40, s40, 0x40000
	s_addc_u32 s41, s41, 0
	v_cvt_pk_bf16_f32 v51, v15, v15
	v_lshlrev_b32_e32 v54, 16, v97
	global_store_short v2, v51, s[40:41]
	v_fma_f32 v15, v105, v15, v54
	s_add_u32 s40, s40, 0x40000
	s_addc_u32 s41, s41, 0
	v_cvt_pk_bf16_f32 v52, v15, v15
	v_lshlrev_b32_e32 v54, 16, v98
	global_store_short v2, v52, s[40:41]
	v_fma_f32 v15, v106, v15, v54
	s_add_u32 s40, s40, 0x40000
	s_addc_u32 s41, s41, 0
	v_cvt_pk_bf16_f32 v53, v15, v15
	v_lshlrev_b32_e32 v54, 16, v99
	global_store_short v2, v53, s[40:41]
	v_fma_f32 v15, v107, v15, v54
	s_add_u32 s40, s40, 0x40000
	s_addc_u32 s41, s41, 0
	s_waitcnt vmcnt(32)
; DI u16 f2bf(float x) { return (u16)(pack2(x, 0.f) & 0xffffu); }
; DI float bf2f(u16 h) { return __uint_as_float(((unsigned)h) << 16); }
; DI void hgrn_scan_phase(const Params& p, char* smem) {
;     ...
;     for (int n0 = 0; n0 < 256; n0 += 8) {
;       float nu[8], nd[8];
;       if (n0 + 8 < 256) {
; #pragma unroll
;         for (int j = 0; j < 8; j++) { nu[j] = bf2f(up[(long)(n0 + 8 + j) * 131072]); nd[j] = dp[(n0 + 8 + j) * 1024]; }
;       } else {
; #pragma unroll
;         for (int j = 0; j < 8; j++) { nu[j] = 0.f; nd[j] = 0.f; }
;       }
; #pragma unroll
;       for (int j = 0; j < 8; j++) { up[(long)(n0 + j) * 131072] = f2bf(S); S = cd[j] * S + cu[j]; }
; #pragma unroll
;       for (int j = 0; j < 8; j++) { cu[j] = nu[j]; cd[j] = nd[j]; }
;     }
	v_cvt_pk_bf16_f32 v50, v15, v15
	v_lshlrev_b32_e32 v54, 16, v60
	global_store_short v2, v50, s[40:41]
	v_fma_f32 v15, v68, v15, v54
	s_add_u32 s40, s40, 0x40000
	s_addc_u32 s41, s41, 0
	v_cvt_pk_bf16_f32 v51, v15, v15
	v_lshlrev_b32_e32 v54, 16, v61
	global_store_short v2, v51, s[40:41]
	v_fma_f32 v15, v69, v15, v54
	s_add_u32 s40, s40, 0x40000
	s_addc_u32 s41, s41, 0
	v_cvt_pk_bf16_f32 v52, v15, v15
	v_lshlrev_b32_e32 v54, 16, v62
	global_store_short v2, v52, s[40:41]
	v_fma_f32 v15, v70, v15, v54
	s_add_u32 s40, s40, 0x40000
	s_addc_u32 s41, s41, 0
	v_cvt_pk_bf16_f32 v53, v15, v15
	v_lshlrev_b32_e32 v54, 16, v63
	global_store_short v2, v53, s[40:41]
	v_fma_f32 v15, v71, v15, v54
	s_add_u32 s40, s40, 0x40000
	s_addc_u32 s41, s41, 0
	v_cvt_pk_bf16_f32 v50, v15, v15
	v_lshlrev_b32_e32 v54, 16, v64
	global_store_short v2, v50, s[40:41]
	v_fma_f32 v15, v72, v15, v54
	s_add_u32 s40, s40, 0x40000
	s_addc_u32 s41, s41, 0
	v_cvt_pk_bf16_f32 v51, v15, v15
	v_lshlrev_b32_e32 v54, 16, v65
	global_store_short v2, v51, s[40:41]
	v_fma_f32 v15, v73, v15, v54
	s_add_u32 s40, s40, 0x40000
	s_addc_u32 s41, s41, 0
	v_cvt_pk_bf16_f32 v52, v15, v15
	v_lshlrev_b32_e32 v54, 16, v66
	global_store_short v2, v52, s[40:41]
	v_fma_f32 v15, v74, v15, v54
	s_add_u32 s40, s40, 0x40000
	s_addc_u32 s41, s41, 0
	v_cvt_pk_bf16_f32 v53, v15, v15
	v_lshlrev_b32_e32 v54, 16, v67
	global_store_short v2, v53, s[40:41]
	v_fma_f32 v15, v75, v15, v54
	s_add_u32 s40, s40, 0x40000
	s_addc_u32 s41, s41, 0
	s_waitcnt vmcnt(16)
	v_cvt_pk_bf16_f32 v50, v15, v15
	v_lshlrev_b32_e32 v54, 16, v76
	global_store_short v2, v50, s[40:41]
	v_fma_f32 v15, v84, v15, v54
	s_add_u32 s40, s40, 0x40000
	s_addc_u32 s41, s41, 0
	v_cvt_pk_bf16_f32 v51, v15, v15
	v_lshlrev_b32_e32 v54, 16, v77
	global_store_short v2, v51, s[40:41]
	v_fma_f32 v15, v85, v15, v54
	s_add_u32 s40, s40, 0x40000
	s_addc_u32 s41, s41, 0
	v_cvt_pk_bf16_f32 v52, v15, v15
	v_lshlrev_b32_e32 v54, 16, v78
	global_store_short v2, v52, s[40:41]
	v_fma_f32 v15, v86, v15, v54
	s_add_u32 s40, s40, 0x40000
	s_addc_u32 s41, s41, 0
	v_cvt_pk_bf16_f32 v53, v15, v15
	v_lshlrev_b32_e32 v54, 16, v79
	global_store_short v2, v53, s[40:41]
	v_fma_f32 v15, v87, v15, v54
	s_add_u32 s40, s40, 0x40000
	s_addc_u32 s41, s41, 0
	v_cvt_pk_bf16_f32 v50, v15, v15
	v_lshlrev_b32_e32 v54, 16, v80
	global_store_short v2, v50, s[40:41]
	v_fma_f32 v15, v88, v15, v54
	s_add_u32 s40, s40, 0x40000
	s_addc_u32 s41, s41, 0
	v_cvt_pk_bf16_f32 v51, v15, v15
	v_lshlrev_b32_e32 v54, 16, v81
	global_store_short v2, v51, s[40:41]
	v_fma_f32 v15, v89, v15, v54
	s_add_u32 s40, s40, 0x40000
	s_addc_u32 s41, s41, 0
	v_cvt_pk_bf16_f32 v52, v15, v15
	v_lshlrev_b32_e32 v54, 16, v82
	global_store_short v2, v52, s[40:41]
	v_fma_f32 v15, v90, v15, v54
	s_add_u32 s40, s40, 0x40000
	s_addc_u32 s41, s41, 0
	v_cvt_pk_bf16_f32 v53, v15, v15
	v_lshlrev_b32_e32 v54, 16, v83
	global_store_short v2, v53, s[40:41]
	v_fma_f32 v15, v91, v15, v54
	s_add_u32 s40, s40, 0x40000
	s_addc_u32 s41, s41, 0
	s_branch .LBB0_1335

; __global__ void __launch_bounds__(256, 2) fwd_megakernel(Params p) {
;   __shared__ __attribute__((aligned(16))) char smem[SMEM_TOTAL];
	.amdhsa_kernel _Z14fwd_megakernel6Params
		.amdhsa_group_segment_fixed_size 73984
		.amdhsa_private_segment_fixed_size 0
		.amdhsa_kernarg_size 752
		.amdhsa_user_sgpr_count 2
		.amdhsa_user_sgpr_dispatch_ptr 0
		.amdhsa_user_sgpr_queue_ptr 0
		.amdhsa_user_sgpr_kernarg_segment_ptr 1
		.amdhsa_user_sgpr_dispatch_id 0
		.amdhsa_user_sgpr_kernarg_preload_length 0
		.amdhsa_user_sgpr_kernarg_preload_offset 0
		.amdhsa_user_sgpr_private_segment_size 0
		.amdhsa_uses_dynamic_stack 0
		.amdhsa_enable_private_segment 0
		.amdhsa_system_sgpr_workgroup_id_x 1
		.amdhsa_system_sgpr_workgroup_id_y 0
		.amdhsa_system_sgpr_workgroup_id_z 0
		.amdhsa_system_sgpr_workgroup_info 0
		.amdhsa_system_vgpr_workitem_id 2
		.amdhsa_next_free_vgpr 256
		.amdhsa_next_free_sgpr 102
		.amdhsa_accum_offset 256
		.amdhsa_reserve_vcc 1
		.amdhsa_float_round_mode_32 0
		.amdhsa_float_round_mode_16_64 0
		.amdhsa_float_denorm_mode_32 3
		.amdhsa_float_denorm_mode_16_64 3
		.amdhsa_dx10_clamp 1
		.amdhsa_ieee_mode 1
		.amdhsa_fp16_overflow 0
		.amdhsa_tg_split 0
		.amdhsa_exception_fp_ieee_invalid_op 0
		.amdhsa_exception_fp_denorm_src 0
		.amdhsa_exception_fp_ieee_div_zero 0
		.amdhsa_exception_fp_ieee_overflow 0
		.amdhsa_exception_fp_ieee_underflow 0
		.amdhsa_exception_fp_ieee_inexact 0
		.amdhsa_exception_int_div_zero 0
	.end_amdhsa_kernel

; __global__ void __launch_bounds__(256, 2) fwd_megakernel(Params p) {
;   __shared__ __attribute__((aligned(16))) char smem[SMEM_TOTAL];
amdhsa.kernels:
  - .agpr_count:     0
    .args:
      - .offset:         0
        .size:           496
        .value_kind:     by_value
      - .offset:         496
        .size:           4
        .value_kind:     hidden_block_count_x
      - .offset:         500
        .size:           4
        .value_kind:     hidden_block_count_y
      - .offset:         504
        .size:           4
        .value_kind:     hidden_block_count_z
      - .offset:         508
        .size:           2
        .value_kind:     hidden_group_size_x
      - .offset:         510
        .size:           2
        .value_kind:     hidden_group_size_y
      - .offset:         512
        .size:           2
        .value_kind:     hidden_group_size_z
      - .offset:         514
        .size:           2
        .value_kind:     hidden_remainder_x
      - .offset:         516
        .size:           2
        .value_kind:     hidden_remainder_y
      - .offset:         518
        .size:           2
        .value_kind:     hidden_remainder_z
      - .offset:         536
        .size:           8
        .value_kind:     hidden_global_offset_x
      - .offset:         544
        .size:           8
        .value_kind:     hidden_global_offset_y
      - .offset:         552
        .size:           8
        .value_kind:     hidden_global_offset_z
      - .offset:         560
        .size:           2
        .value_kind:     hidden_grid_dims
      - .offset:         584
        .size:           8
        .value_kind:     hidden_multigrid_sync_arg
    .group_segment_fixed_size: 73984
    .kernarg_segment_align: 8
    .kernarg_segment_size: 752
    .language:       OpenCL C
    .language_version:
      - 2
      - 0
    .max_flat_workgroup_size: 256
    .name:           _Z14fwd_megakernel6Params
    .private_segment_fixed_size: 0
    .sgpr_count:     108
    .sgpr_spill_count: 39
    .symbol:         _Z14fwd_megakernel6Params.kd
    .uniform_work_group_size: 1
    .uses_dynamic_stack: false
    .vgpr_count:     256
    .vgpr_spill_count: 0
    .wavefront_size: 64
